# v026 + attention z-gate tile staged in LDS (DMA in drain iteration), epilogue loads -> ds_read_u16 with counted lgkmcnt waits derived by stream simulation
# speedup vs baseline: 1.0013x; 1.0013x over previous
; DI float bf2f(unsigned short u) { return __uint_as_float((unsigned)u << 16); }
; DI unsigned f2bf(float f) { unsigned u = __float_as_uint(f); return (u + 0x7fffu + ((u >> 16) & 1u)) >> 16; }
; DI int crow(int i, int hh) { return (i & 3) + 8 * (i >> 2) + 4 * hh; }
; DI void attn_unit(Ctx A_, LAS unsigned char* lds, int b, int h, int qb, float lam, int wave, int lane) {
;     ...
;     asm volatile("s_waitcnt lgkmcnt(0)" ::: "memory"); __builtin_amdgcn_s_barrier(); asm volatile("" ::: "memory");
;     if (mp == 0) {
;         float ssq[16];
; #pragma unroll
;         for (int i = 0; i < 16; ++i) ssq[i] = 0.f;
; #pragma unroll
;         for (int nb = 0; nb < 4; ++nb)
; #pragma unroll
;             for (int i = 0; i < 16; ++i) { const float d = o[nb][i] - X2[(nb * 16 + i) * 64]; o[nb][i] = d; ssq[i] += d * d; }
; #pragma unroll
;         for (int i = 0; i < 16; ++i) {
;             float v = ssq[i];
; #pragma unroll
;             for (int x = 1; x < 32; x <<= 1) v += __shfl_xor(v, x);
;             ssq[i] = ONE_M_LAMINIT / sqrtf(v * (1.0f / 128.0f) + NORM_EPS);
;         }
; #pragma unroll
;         for (int nb = 0; nb < 4; ++nb) {
;             const float sn = SUB_NORM[nb * 32 + r_e];
; #pragma unroll
;             for (int i = 0; i < 16; ++i) {
;                 const size_t rw = (size_t)(rowq_e + crow(i, hh_e));
;                 Y_[rw * YLD + C_YA + h_e * 128 + nb * 32 + r_e] = (bf16)f2bf(o[nb][i] * ssq[i] * sn * bf2f(P[rw * PLD + C_ZA + h_e * 128 + nb * 32 + r_e]));
;             }
;         }
;     }
.LBB0_894:
	s_waitcnt lgkmcnt(0)
	s_barrier
	v_readlane_b32 s4, v255, 36
	v_readlane_b32 s5, v255, 37
	s_andn2_b64 vcc, exec, s[4:5]
	s_cbranch_vccnz .LBB0_862
	s_mul_i32 s99, s0, 0x5800
	v_readlane_b32 s98, v255, 9
	s_add_u32 s99, s99, s98
	s_lshl_b32 s98, s63, 8
	s_add_u32 s99, s99, s98
	s_addk_i32 s99, 0x1800
	s_sub_u32 s99, 0, s99
	s_add_u32 s98, s99, 0x800
	v_readfirstlane_b32 s100, v0
	s_lshr_b32 s100, s100, 6
	s_lshl_b32 s100, s100, 13
	s_add_u32 s100, s100, 0x10000
	s_mov_b32 s101, 0x2e8bb
	ds_read2st64_b32 v[4:5], v64 offset1:1
	ds_read2st64_b32 v[24:25], v64 offset0:2 offset1:3
	ds_read2st64_b32 v[18:19], v64 offset0:4 offset1:5
	ds_read2st64_b32 v[16:17], v64 offset0:6 offset1:7
	ds_read2st64_b32 v[32:33], v64 offset0:16 offset1:17
	s_waitcnt lgkmcnt(4)
	v_sub_f32_e32 v104, v34, v4
	ds_read2st64_b32 v[26:27], v64 offset0:18 offset1:19
	ds_read2st64_b32 v[14:15], v64 offset0:20 offset1:21
	ds_read2st64_b32 v[10:11], v64 offset0:22 offset1:23
	v_readlane_b32 s64, v254, 22
	v_readlane_b32 s74, v254, 32
	s_waitcnt lgkmcnt(3)
	v_sub_f32_e32 v97, v35, v32
	ds_read2st64_b32 v[34:35], v64 offset0:32 offset1:33
	ds_read2st64_b32 v[28:29], v64 offset0:34 offset1:35
	ds_read2st64_b32 v[20:21], v64 offset0:36 offset1:37
	ds_read2st64_b32 v[8:9], v64 offset0:38 offset1:39
	v_readlane_b32 s75, v254, 33
	v_mul_f32_e32 v3, v97, v97
	v_fmac_f32_e32 v3, v104, v104
	s_waitcnt lgkmcnt(3)
	v_sub_f32_e32 v98, v36, v34
	ds_read2st64_b32 v[36:37], v64 offset0:48 offset1:49
	ds_read2st64_b32 v[30:31], v64 offset0:50 offset1:51
	ds_read2st64_b32 v[22:23], v64 offset0:52 offset1:53
	ds_read2st64_b32 v[12:13], v64 offset0:54 offset1:55
	v_fmac_f32_e32 v3, v98, v98
	v_readlane_b32 s4, v255, 9
	v_readlane_b32 s5, v255, 10
	s_waitcnt lgkmcnt(3)
	v_sub_f32_e32 v99, v2, v36
	v_lshl_add_u32 v36, v197, 2, s0
	v_ashrrev_i32_e32 v197, 31, v196
	v_lshl_add_u64 v[38:39], v[196:197], 2, s[74:75]
	global_load_dword v34, v[38:39], off
	v_fmac_f32_e32 v3, v99, v99
	s_nop 1
	v_mov_b32_dpp v2, v3 quad_perm:[1,0,3,2] row_mask:0xf bank_mask:0xf
	s_lshl_b32 s0, s63, 7
	s_ashr_i32 s1, s0, 31
	v_mov_b64_e32 v[6:7], s[4:5]
	s_lshl_b64 s[0:1], s[0:1], 1
	v_mad_i64_i32 v[106:107], s[4:5], v36, s57, v[6:7]
	s_waitcnt lgkmcnt(0)
	v_add_f32_e32 v4, v3, v2
	v_lshlrev_b64 v[2:3], 1, v[196:197]
	v_lshl_add_u64 v[106:107], v[106:107], 0, s[0:1]
	v_lshl_add_u64 v[110:111], v[106:107], 0, v[2:3]
	v_add_co_u32_e32 v106, vcc, s60, v110
	s_nop 1
	v_mov_b32_dpp v32, v4 quad_perm:[2,3,0,1] row_mask:0xf bank_mask:0xf
	s_nop 0
	v_addc_co_u32_e32 v107, vcc, 0, v111, vcc
	v_add_u32_e32 v206, s98, v106
	v_mul_hi_u32 v207, v206, s101
	v_mul_u32_u24_e32 v207, 0x5700, v207
	v_sub_u32_e32 v206, v206, v207
	v_add_u32_e32 v206, s100, v206
	ds_read_u16 v107, v206
	v_sub_f32_e32 v106, v100, v5
	s_waitcnt lgkmcnt(0)
	v_add_f32_e32 v4, v4, v32
	s_nop 1
	v_mov_b32_dpp v32, v4 row_half_mirror row_mask:0xf bank_mask:0xf
	v_sub_f32_e32 v105, v101, v33
	v_sub_f32_e32 v100, v102, v35
	v_sub_f32_e32 v101, v103, v37
	v_sub_f32_e32 v24, v93, v24
	s_waitcnt lgkmcnt(0)
	v_add_f32_e32 v4, v4, v32
	s_nop 1
	v_mov_b32_dpp v32, v4 row_mirror row_mask:0xf bank_mask:0xf
	v_sub_f32_e32 v30, v96, v30
	v_sub_f32_e32 v89, v89, v25
	v_sub_f32_e32 v91, v91, v29
	v_sub_f32_e32 v92, v92, v31
	s_waitcnt lgkmcnt(0)
	v_add_f32_e32 v4, v4, v32
	ds_bpermute_b32 v5, v209, v4
	v_mul_f32_e32 v32, v105, v105
	v_fmac_f32_e32 v32, v106, v106
	v_fmac_f32_e32 v32, v100, v100
	v_fmac_f32_e32 v32, v101, v101
	s_waitcnt lgkmcnt(0)
	v_add_f32_e32 v4, v4, v5
	v_fmamk_f32 v4, v4, 0x3c000000, v211
	v_mul_f32_e32 v5, 0x4f800000, v4
	v_cmp_gt_f32_e32 vcc, s58, v4
	v_sub_f32_e32 v90, v90, v27
	v_mul_f32_e32 v27, v90, v90
	v_cndmask_b32_e32 v4, v4, v5, vcc
	v_sqrt_f32_e32 v5, v4
	v_fmac_f32_e32 v27, v89, v89
	v_fmac_f32_e32 v27, v91, v91
	v_fmac_f32_e32 v27, v92, v92
	v_add_u32_e32 v33, -1, v5
	v_fma_f32 v35, -v33, v5, v4
	v_cmp_ge_f32_e64 s[4:5], 0, v35
	v_add_u32_e32 v35, 1, v5
	v_sub_f32_e32 v88, v88, v18
	v_cndmask_b32_e64 v33, v5, v33, s[4:5]
	v_fma_f32 v5, -v35, v5, v4
	v_cmp_lt_f32_e64 s[4:5], 0, v5
	v_sub_f32_e32 v84, v84, v16
	v_sub_f32_e32 v83, v83, v19
	v_cndmask_b32_e64 v5, v33, v35, s[4:5]
	s_nop 1
	v_mov_b32_dpp v35, v32 quad_perm:[1,0,3,2] row_mask:0xf bank_mask:0xf
	v_mul_f32_e32 v33, 0x37800000, v5
	v_cndmask_b32_e32 v5, v5, v33, vcc
	v_cmp_class_f32_e32 vcc, v4, v212
	v_sub_f32_e32 v86, v86, v20
	s_waitcnt lgkmcnt(0)
	v_add_f32_e32 v32, v32, v35
	v_cndmask_b32_e32 v4, v5, v4, vcc
	v_div_scale_f32 v5, s[4:5], v4, v4, s59
	s_nop 1
	v_mov_b32_dpp v35, v32 quad_perm:[2,3,0,1] row_mask:0xf bank_mask:0xf
	v_rcp_f32_e32 v33, v5
	s_add_u32 s4, s51, s0
	s_addc_u32 s5, s52, s1
	v_sub_f32_e32 v85, v85, v14
	v_fma_f32 v37, -v5, v33, 1.0
	s_waitcnt lgkmcnt(0)
	v_add_f32_e32 v32, v32, v35
	v_fmac_f32_e32 v33, v37, v33
	v_div_scale_f32 v37, vcc, s59, v4, s59
	s_nop 1
	v_mov_b32_dpp v35, v32 row_half_mirror row_mask:0xf bank_mask:0xf
	v_mul_f32_e32 v102, v37, v33
	v_fma_f32 v103, -v5, v102, v37
	v_fmac_f32_e32 v102, v103, v33
	v_fma_f32 v5, -v5, v102, v37
	v_div_fmas_f32 v5, v5, v33, v102
	s_waitcnt lgkmcnt(0)
	v_add_f32_e32 v103, v32, v35
	v_lshl_add_u64 v[32:33], v[110:111], 0, s[20:21]
	global_load_dword v35, v[38:39], off offset:128
	v_add_u32_e32 v206, s99, v32
	v_mul_hi_u32 v207, v206, s101
	v_mul_u32_u24_e32 v207, 0x5700, v207
	v_sub_u32_e32 v206, v206, v207
	v_add_u32_e32 v206, s100, v206
	ds_read_u16 v109, v206 offset:64
	global_load_dword v37, v[38:39], off offset:256
	s_nop 0
	global_load_dword v38, v[38:39], off offset:384
	s_waitcnt vmcnt(0)
; DI float bf2f(unsigned short u) { return __uint_as_float((unsigned)u << 16); }
; DI unsigned f2bf(float f) { unsigned u = __float_as_uint(f); return (u + 0x7fffu + ((u >> 16) & 1u)) >> 16; }
; DI int crow(int i, int hh) { return (i & 3) + 8 * (i >> 2) + 4 * hh; }
; DI void attn_unit(Ctx A_, LAS unsigned char* lds, int b, int h, int qb, float lam, int wave, int lane) {
;     ...
;     if (mp == 0) {
;         float ssq[16];
; #pragma unroll
;         for (int i = 0; i < 16; ++i) ssq[i] = 0.f;
; #pragma unroll
;         for (int nb = 0; nb < 4; ++nb)
; #pragma unroll
;             for (int i = 0; i < 16; ++i) { const float d = o[nb][i] - X2[(nb * 16 + i) * 64]; o[nb][i] = d; ssq[i] += d * d; }
; #pragma unroll
;         for (int i = 0; i < 16; ++i) {
;             float v = ssq[i];
; #pragma unroll
;             for (int x = 1; x < 32; x <<= 1) v += __shfl_xor(v, x);
;             ssq[i] = ONE_M_LAMINIT / sqrtf(v * (1.0f / 128.0f) + NORM_EPS);
;         }
; #pragma unroll
;         for (int nb = 0; nb < 4; ++nb) {
;             const float sn = SUB_NORM[nb * 32 + r_e];
; #pragma unroll
;             for (int i = 0; i < 16; ++i) {
;                 const size_t rw = (size_t)(rowq_e + crow(i, hh_e));
;                 Y_[rw * YLD + C_YA + h_e * 128 + nb * 32 + r_e] = (bf16)f2bf(o[nb][i] * ssq[i] * sn * bf2f(P[rw * PLD + C_ZA + h_e * 128 + nb * 32 + r_e]));
;             }
;         }
;     }
	v_div_fixup_f32 v102, v5, v4, s59
	v_mul_f32_e32 v104, v104, v102
	v_mul_f32_e32 v39, v104, v34
	v_add_u32_e32 v206, s99, v32
	v_mul_hi_u32 v207, v206, s101
	v_mul_u32_u24_e32 v207, 0x5700, v207
	v_sub_u32_e32 v206, v206, v207
	v_add_u32_e32 v206, s100, v206
	ds_read_u16 v104, v206 offset:128
	v_add_u32_e32 v206, s99, v32
	v_mul_hi_u32 v207, v206, s101
	v_mul_u32_u24_e32 v207, 0x5700, v207
	v_sub_u32_e32 v206, v206, v207
	v_add_u32_e32 v206, s100, v206
	ds_read_u16 v114, v206 offset:192
	v_lshl_add_u64 v[4:5], s[4:5], 0, v[2:3]
	s_nop 1
	v_mov_b32_dpp v108, v103 row_mirror row_mask:0xf bank_mask:0xf
	v_mul_f32_e32 v97, v97, v102
	v_mul_f32_e32 v14, v85, v85
	v_fmac_f32_e32 v14, v88, v88
	v_fmac_f32_e32 v14, v86, v86
	v_lshlrev_b32_e32 v32, 16, v107
	v_mul_f32_e32 v32, v39, v32
	v_bfe_u32 v33, v32, 16, 1
	v_add3_u32 v39, v32, v33, s61
	v_mad_i64_i32 v[32:33], s[4:5], v36, s62, v[4:5]
	global_store_short_d16_hi v[32:33], v39, off
	v_add_u32_e32 v39, 1, v36
	v_mad_i64_i32 v[110:111], s[4:5], v39, s57, v[6:7]
	v_lshl_add_u64 v[110:111], v[110:111], 0, s[0:1]
	v_lshl_add_u64 v[110:111], v[110:111], 0, v[2:3]
	v_add_co_u32_e32 v112, vcc, s60, v110
	s_waitcnt lgkmcnt(0)
	v_add_f32_e32 v93, v103, v108
	v_addc_co_u32_e32 v113, vcc, 0, v111, vcc
	v_add_u32_e32 v206, s98, v112
	v_mul_hi_u32 v207, v206, s101
	v_mul_u32_u24_e32 v207, 0x5700, v207
	v_sub_u32_e32 v206, v206, v207
	v_add_u32_e32 v206, s100, v206
	ds_read_u16 v107, v206
	ds_bpermute_b32 v103, v209, v93
	v_sub_f32_e32 v112, v95, v28
	v_sub_f32_e32 v108, v94, v26
	v_mul_f32_e32 v26, v108, v108
	v_fmac_f32_e32 v26, v24, v24
	s_waitcnt lgkmcnt(0)
	v_add_f32_e32 v28, v93, v103
	v_fmamk_f32 v28, v28, 0x3c000000, v211
	v_mul_f32_e32 v93, 0x4f800000, v28
	v_cmp_gt_f32_e32 vcc, s58, v28
	v_fmac_f32_e32 v26, v112, v112
	v_fmac_f32_e32 v26, v30, v30
	v_cndmask_b32_e32 v28, v28, v93, vcc
	v_sqrt_f32_e32 v93, v28
	v_sub_f32_e32 v87, v87, v22
	v_fmac_f32_e32 v14, v87, v87
	v_sub_f32_e32 v82, v82, v17
	v_add_u32_e32 v94, -1, v93
	v_fma_f32 v95, -v94, v93, v28
	v_cmp_ge_f32_e64 s[4:5], 0, v95
	v_add_u32_e32 v95, 1, v93
	v_readlane_b32 s65, v254, 23
	v_cndmask_b32_e64 v94, v93, v94, s[4:5]
	v_fma_f32 v93, -v95, v93, v28
	v_cmp_lt_f32_e64 s[4:5], 0, v93
	v_readlane_b32 s66, v254, 24
	v_readlane_b32 s67, v254, 25
	v_cndmask_b32_e64 v93, v94, v95, s[4:5]
	v_mul_f32_e32 v94, 0x37800000, v93
	v_cndmask_b32_e32 v93, v93, v94, vcc
	v_cmp_class_f32_e32 vcc, v28, v212
	s_nop 1
	v_mov_b32_dpp v95, v26 quad_perm:[1,0,3,2] row_mask:0xf bank_mask:0xf
	v_readlane_b32 s68, v254, 26
	v_cndmask_b32_e32 v28, v93, v28, vcc
	v_div_scale_f32 v93, s[4:5], v28, v28, s59
	v_rcp_f32_e32 v94, v93
	s_waitcnt lgkmcnt(0)
	v_add_f32_e32 v26, v26, v95
	s_nop 1
	v_mov_b32_dpp v95, v26 quad_perm:[2,3,0,1] row_mask:0xf bank_mask:0xf
	v_readlane_b32 s69, v254, 27
	v_fma_f32 v96, -v93, v94, 1.0
	v_fmac_f32_e32 v94, v96, v94
	v_div_scale_f32 v96, vcc, s59, v28, s59
	v_mul_f32_e32 v103, v96, v94
	v_fma_f32 v113, -v93, v103, v96
	v_fmac_f32_e32 v103, v113, v94
	v_fma_f32 v93, -v93, v103, v96
	v_div_fmas_f32 v93, v93, v94, v103
	v_mul_f32_e32 v97, v97, v35
	v_lshlrev_b32_e32 v103, 16, v109
	v_mul_f32_e32 v97, v97, v103
	s_waitcnt lgkmcnt(0)
	v_add_f32_e32 v26, v26, v95
	v_bfe_u32 v103, v97, 16, 1
	s_nop 1
	v_mov_b32_dpp v95, v26 row_half_mirror row_mask:0xf bank_mask:0xf
	v_add3_u32 v97, v97, v103, s61
	global_store_short_d16_hi v[32:33], v97, off offset:64
	v_mul_f32_e32 v97, v98, v102
	v_mul_f32_e32 v97, v97, v37
	v_lshlrev_b32_e32 v98, 16, v104
	v_div_fixup_f32 v28, v93, v28, s59
	v_mul_f32_e32 v97, v97, v98
	v_mul_f32_e32 v94, v106, v28
	v_bfe_u32 v98, v97, 16, 1
	s_waitcnt lgkmcnt(0)
	v_add_f32_e32 v26, v26, v95
	v_mul_f32_e32 v96, v94, v34
	v_lshl_add_u64 v[94:95], v[110:111], 0, s[20:21]
	v_add3_u32 v97, v97, v98, s61
	v_add_u32_e32 v206, s99, v94
	v_mul_hi_u32 v207, v206, s101
	v_mul_u32_u24_e32 v207, 0x5700, v207
	v_sub_u32_e32 v206, v206, v207
	v_add_u32_e32 v206, s100, v206
	ds_read_u16 v103, v206 offset:64
	v_lshlrev_b32_e32 v98, 16, v114
	global_store_short_d16_hi v[32:33], v97, off offset:128
	v_mul_f32_e32 v97, v99, v102
	v_mul_f32_e32 v97, v97, v38
	v_mul_f32_e32 v97, v97, v98
	v_bfe_u32 v98, v97, 16, 1
	v_add3_u32 v97, v97, v98, s61
	global_store_short_d16_hi v[32:33], v97, off offset:192
	v_add_u32_e32 v206, s99, v94
	v_mul_hi_u32 v207, v206, s101
	v_mul_u32_u24_e32 v207, 0x5700, v207
	v_sub_u32_e32 v206, v206, v207
	v_add_u32_e32 v206, s100, v206
	ds_read_u16 v98, v206 offset:128
	v_add_u32_e32 v206, s99, v94
	v_mul_hi_u32 v207, v206, s101
	v_mul_u32_u24_e32 v207, 0x5700, v207
	v_sub_u32_e32 v206, v206, v207
	v_add_u32_e32 v206, s100, v206
	ds_read_u16 v99, v206 offset:192
	s_nop 1
	v_mov_b32_dpp v93, v26 row_mirror row_mask:0xf bank_mask:0xf
	v_readlane_b32 s70, v254, 28
	v_lshlrev_b32_e32 v32, 16, v107
	v_mul_f32_e32 v32, v96, v32
	v_bfe_u32 v33, v32, 16, 1
	v_add3_u32 v94, v32, v33, s61
	v_mad_i64_i32 v[32:33], s[4:5], v39, s62, v[4:5]
	v_add_u32_e32 v39, 2, v36
	global_store_short_d16_hi v[32:33], v94, off
	v_mad_i64_i32 v[94:95], s[4:5], v39, s57, v[6:7]
	v_lshl_add_u64 v[94:95], v[94:95], 0, s[0:1]
	v_lshl_add_u64 v[94:95], v[94:95], 0, v[2:3]
	v_add_co_u32_e32 v96, vcc, s60, v94
	s_waitcnt lgkmcnt(0)
	v_add_f32_e32 v25, v26, v93
	v_addc_co_u32_e32 v97, vcc, 0, v95, vcc
	v_add_u32_e32 v206, s98, v96
	v_mul_hi_u32 v207, v206, s101
	v_mul_u32_u24_e32 v207, 0x5700, v207
	v_sub_u32_e32 v206, v206, v207
	v_add_u32_e32 v206, s100, v206
	ds_read_u16 v96, v206
	ds_bpermute_b32 v26, v209, v25
	v_readlane_b32 s71, v254, 29
	v_readlane_b32 s72, v254, 30
	v_readlane_b32 s73, v254, 31
	v_readlane_b32 s76, v254, 34
	s_waitcnt lgkmcnt(0)
; DI float bf2f(unsigned short u) { return __uint_as_float((unsigned)u << 16); }
; DI unsigned f2bf(float f) { unsigned u = __float_as_uint(f); return (u + 0x7fffu + ((u >> 16) & 1u)) >> 16; }
; DI int crow(int i, int hh) { return (i & 3) + 8 * (i >> 2) + 4 * hh; }
; DI void attn_unit(Ctx A_, LAS unsigned char* lds, int b, int h, int qb, float lam, int wave, int lane) {
;     ...
;     if (mp == 0) {
;         float ssq[16];
; #pragma unroll
;         for (int i = 0; i < 16; ++i) ssq[i] = 0.f;
; #pragma unroll
;         for (int nb = 0; nb < 4; ++nb)
; #pragma unroll
;             for (int i = 0; i < 16; ++i) { const float d = o[nb][i] - X2[(nb * 16 + i) * 64]; o[nb][i] = d; ssq[i] += d * d; }
; #pragma unroll
;         for (int i = 0; i < 16; ++i) {
;             float v = ssq[i];
; #pragma unroll
;             for (int x = 1; x < 32; x <<= 1) v += __shfl_xor(v, x);
;             ssq[i] = ONE_M_LAMINIT / sqrtf(v * (1.0f / 128.0f) + NORM_EPS);
;         }
; #pragma unroll
;         for (int nb = 0; nb < 4; ++nb) {
;             const float sn = SUB_NORM[nb * 32 + r_e];
; #pragma unroll
;             for (int i = 0; i < 16; ++i) {
;                 const size_t rw = (size_t)(rowq_e + crow(i, hh_e));
;                 Y_[rw * YLD + C_YA + h_e * 128 + nb * 32 + r_e] = (bf16)f2bf(o[nb][i] * ssq[i] * sn * bf2f(P[rw * PLD + C_ZA + h_e * 128 + nb * 32 + r_e]));
;             }
;         }
;     }
	v_add_f32_e32 v25, v25, v26
	v_fmamk_f32 v25, v25, 0x3c000000, v211
	v_mul_f32_e32 v26, 0x4f800000, v25
	v_cmp_gt_f32_e32 vcc, s58, v25
	v_readlane_b32 s77, v254, 35
	v_readlane_b32 s78, v254, 36
	v_cndmask_b32_e32 v25, v25, v26, vcc
	v_sqrt_f32_e32 v26, v25
	v_readlane_b32 s79, v254, 37
	v_add_u32_e32 v29, -1, v26
	v_fma_f32 v31, -v29, v26, v25
	v_cmp_ge_f32_e64 s[4:5], 0, v31
	v_add_u32_e32 v31, 1, v26
	s_nop 0
	v_cndmask_b32_e64 v29, v26, v29, s[4:5]
	v_fma_f32 v26, -v31, v26, v25
	v_cmp_lt_f32_e64 s[4:5], 0, v26
	s_nop 1
	v_cndmask_b32_e64 v26, v29, v31, s[4:5]
	v_mul_f32_e32 v29, 0x37800000, v26
	v_cndmask_b32_e32 v26, v26, v29, vcc
	v_cmp_class_f32_e32 vcc, v25, v212
	s_nop 1
	v_mov_b32_dpp v31, v27 quad_perm:[1,0,3,2] row_mask:0xf bank_mask:0xf
	s_nop 0
	v_cndmask_b32_e32 v25, v26, v25, vcc
	v_div_scale_f32 v26, s[4:5], v25, v25, s59
	v_rcp_f32_e32 v29, v26
	s_nop 0
	v_fma_f32 v18, -v26, v29, 1.0
	v_fmac_f32_e32 v29, v18, v29
	s_waitcnt lgkmcnt(0)
	v_add_f32_e32 v18, v27, v31
	s_nop 1
	v_mov_b32_dpp v27, v18 quad_perm:[2,3,0,1] row_mask:0xf bank_mask:0xf
	v_div_scale_f32 v31, vcc, s59, v25, s59
	v_mul_f32_e32 v93, v31, v29
	v_fma_f32 v97, -v26, v93, v31
	s_waitcnt lgkmcnt(0)
	v_add_f32_e32 v18, v18, v27
	s_nop 1
	v_mov_b32_dpp v27, v18 row_half_mirror row_mask:0xf bank_mask:0xf
	v_fmac_f32_e32 v93, v97, v29
	v_fma_f32 v26, -v26, v93, v31
	v_div_fmas_f32 v26, v26, v29, v93
	v_lshlrev_b32_e32 v29, 16, v103
	s_waitcnt lgkmcnt(0)
	v_add_f32_e32 v18, v18, v27
	v_mul_f32_e32 v27, v105, v28
	v_mul_f32_e32 v27, v27, v35
	v_mul_f32_e32 v27, v27, v29
	v_bfe_u32 v29, v27, 16, 1
	v_add3_u32 v27, v27, v29, s61
	global_store_short_d16_hi v[32:33], v27, off offset:64
	v_mul_f32_e32 v27, v100, v28
	v_mul_f32_e32 v27, v27, v37
	v_lshlrev_b32_e32 v29, 16, v98
	v_div_fixup_f32 v31, v26, v25, s59
	v_mul_f32_e32 v27, v27, v29
	v_mul_f32_e32 v24, v24, v31
	v_bfe_u32 v29, v27, 16, 1
	v_mul_f32_e32 v26, v24, v34
	v_lshl_add_u64 v[24:25], v[94:95], 0, s[20:21]
	v_add3_u32 v27, v27, v29, s61
	v_add_u32_e32 v206, s99, v24
	v_mul_hi_u32 v207, v206, s101
	v_mul_u32_u24_e32 v207, 0x5700, v207
	v_sub_u32_e32 v206, v206, v207
	v_add_u32_e32 v206, s100, v206
	ds_read_u16 v94, v206 offset:64
	s_nop 1
	v_mov_b32_dpp v93, v18 row_mirror row_mask:0xf bank_mask:0xf
	global_store_short_d16_hi v[32:33], v27, off offset:128
	v_mul_f32_e32 v27, v101, v28
	v_mul_f32_e32 v27, v27, v38
	v_lshlrev_b32_e32 v28, 16, v99
	v_mul_f32_e32 v27, v27, v28
	v_bfe_u32 v28, v27, 16, 1
	v_add3_u32 v27, v27, v28, s61
	global_store_short_d16_hi v[32:33], v27, off offset:192
	v_add_u32_e32 v206, s99, v24
	v_mul_hi_u32 v207, v206, s101
	v_mul_u32_u24_e32 v207, 0x5700, v207
	v_sub_u32_e32 v206, v206, v207
	v_add_u32_e32 v206, s100, v206
	ds_read_u16 v32, v206 offset:128
	s_nop 0
	v_add_u32_e32 v206, s99, v24
	v_mul_hi_u32 v207, v206, s101
	v_mul_u32_u24_e32 v207, 0x5700, v207
	v_sub_u32_e32 v206, v206, v207
	v_add_u32_e32 v206, s100, v206
	ds_read_u16 v33, v206 offset:192
	v_lshlrev_b32_e32 v24, 16, v96
	v_mul_f32_e32 v24, v26, v24
	v_bfe_u32 v25, v24, 16, 1
	v_add3_u32 v26, v24, v25, s61
	v_mad_i64_i32 v[24:25], s[4:5], v39, s62, v[4:5]
	v_add_u32_e32 v39, 3, v36
	global_store_short_d16_hi v[24:25], v26, off
	v_mad_i64_i32 v[26:27], s[4:5], v39, s57, v[6:7]
	v_lshl_add_u64 v[26:27], v[26:27], 0, s[0:1]
	v_lshl_add_u64 v[28:29], v[26:27], 0, v[2:3]
	v_add_co_u32_e32 v26, vcc, s60, v28
	s_waitcnt lgkmcnt(0)
	v_add_f32_e32 v16, v18, v93
	v_addc_co_u32_e32 v27, vcc, 0, v29, vcc
	v_add_u32_e32 v206, s98, v26
	v_mul_hi_u32 v207, v206, s101
	v_mul_u32_u24_e32 v207, 0x5700, v207
	v_sub_u32_e32 v206, v206, v207
	v_add_u32_e32 v206, s100, v206
	ds_read_u16 v95, v206
	ds_bpermute_b32 v18, v209, v16
	s_waitcnt lgkmcnt(0)
	v_add_f32_e32 v16, v16, v18
	v_fmamk_f32 v16, v16, 0x3c000000, v211
	v_mul_f32_e32 v18, 0x4f800000, v16
	v_cmp_gt_f32_e32 vcc, s58, v16
	s_nop 1
	v_cndmask_b32_e32 v16, v16, v18, vcc
	v_sqrt_f32_e32 v18, v16
	s_nop 0
	v_add_u32_e32 v19, -1, v18
	v_fma_f32 v20, -v19, v18, v16
	v_cmp_ge_f32_e64 s[4:5], 0, v20
	v_add_u32_e32 v20, 1, v18
	s_nop 0
	v_cndmask_b32_e64 v19, v18, v19, s[4:5]
	v_fma_f32 v18, -v20, v18, v16
	v_cmp_lt_f32_e64 s[4:5], 0, v18
	s_nop 1
	v_cndmask_b32_e64 v18, v19, v20, s[4:5]
	v_mul_f32_e32 v19, 0x37800000, v18
	v_cndmask_b32_e32 v18, v18, v19, vcc
	v_cmp_class_f32_e32 vcc, v16, v212
	s_nop 1
	v_mov_b32_dpp v20, v14 quad_perm:[1,0,3,2] row_mask:0xf bank_mask:0xf
	s_waitcnt lgkmcnt(0)
	v_add_f32_e32 v14, v14, v20
	v_cndmask_b32_e32 v16, v18, v16, vcc
	v_div_scale_f32 v18, s[4:5], v16, v16, s59
	v_rcp_f32_e32 v19, v18
	v_div_scale_f32 v20, vcc, s59, v16, s59
	v_fma_f32 v17, -v18, v19, 1.0
	v_fmac_f32_e32 v19, v17, v19
	s_nop 1
	v_mov_b32_dpp v17, v14 quad_perm:[2,3,0,1] row_mask:0xf bank_mask:0xf
	v_mul_f32_e32 v22, v20, v19
	v_fma_f32 v93, -v18, v22, v20
	v_fmac_f32_e32 v22, v93, v19
	v_fma_f32 v18, -v18, v22, v20
	s_waitcnt lgkmcnt(0)
	v_add_f32_e32 v14, v14, v17
	s_nop 1
	v_mov_b32_dpp v17, v14 row_half_mirror row_mask:0xf bank_mask:0xf
	v_div_fmas_f32 v18, v18, v19, v22
	v_div_fixup_f32 v20, v18, v16, s59
	v_mul_f32_e32 v16, v89, v20
	v_mul_f32_e32 v19, v108, v31
	s_waitcnt lgkmcnt(0)
; DI float bf2f(unsigned short u) { return __uint_as_float((unsigned)u << 16); }
; DI unsigned f2bf(float f) { unsigned u = __float_as_uint(f); return (u + 0x7fffu + ((u >> 16) & 1u)) >> 16; }
; DI int crow(int i, int hh) { return (i & 3) + 8 * (i >> 2) + 4 * hh; }
; DI void attn_unit(Ctx A_, LAS unsigned char* lds, int b, int h, int qb, float lam, int wave, int lane) {
;     ...
;     if (mp == 0) {
;         float ssq[16];
; #pragma unroll
;         for (int i = 0; i < 16; ++i) ssq[i] = 0.f;
; #pragma unroll
;         for (int nb = 0; nb < 4; ++nb)
; #pragma unroll
;             for (int i = 0; i < 16; ++i) { const float d = o[nb][i] - X2[(nb * 16 + i) * 64]; o[nb][i] = d; ssq[i] += d * d; }
; #pragma unroll
;         for (int i = 0; i < 16; ++i) {
;             float v = ssq[i];
; #pragma unroll
;             for (int x = 1; x < 32; x <<= 1) v += __shfl_xor(v, x);
;             ssq[i] = ONE_M_LAMINIT / sqrtf(v * (1.0f / 128.0f) + NORM_EPS);
;         }
; #pragma unroll
;         for (int nb = 0; nb < 4; ++nb) {
;             const float sn = SUB_NORM[nb * 32 + r_e];
; #pragma unroll
;             for (int i = 0; i < 16; ++i) {
;                 const size_t rw = (size_t)(rowq_e + crow(i, hh_e));
;                 Y_[rw * YLD + C_YA + h_e * 128 + nb * 32 + r_e] = (bf16)f2bf(o[nb][i] * ssq[i] * sn * bf2f(P[rw * PLD + C_ZA + h_e * 128 + nb * 32 + r_e]));
;             }
;         }
;     }
	v_add_f32_e32 v14, v14, v17
	v_mul_f32_e32 v18, v16, v34
	v_lshl_add_u64 v[16:17], v[28:29], 0, s[20:21]
	v_mul_f32_e32 v19, v19, v35
	v_lshlrev_b32_e32 v28, 16, v94
	v_mul_f32_e32 v19, v19, v28
	v_bfe_u32 v28, v19, 16, 1
	v_add3_u32 v19, v19, v28, s61
	global_store_short_d16_hi v[24:25], v19, off offset:64
	v_mul_f32_e32 v19, v112, v31
	v_mul_f32_e32 v19, v19, v37
	v_lshlrev_b32_e32 v28, 16, v32
	v_mul_f32_e32 v19, v19, v28
	v_bfe_u32 v28, v19, 16, 1
	v_add3_u32 v19, v19, v28, s61
	v_add_u32_e32 v206, s99, v16
	v_mul_hi_u32 v207, v206, s101
	v_mul_u32_u24_e32 v207, 0x5700, v207
	v_sub_u32_e32 v206, v206, v207
	v_add_u32_e32 v206, s100, v206
	ds_read_u16 v89, v206 offset:64
	v_lshlrev_b32_e32 v28, 16, v33
	global_store_short_d16_hi v[24:25], v19, off offset:128
	v_mul_f32_e32 v19, v30, v31
	v_mul_f32_e32 v19, v19, v38
	v_mul_f32_e32 v19, v19, v28
	v_bfe_u32 v28, v19, 16, 1
	v_add3_u32 v19, v19, v28, s61
	global_store_short_d16_hi v[24:25], v19, off offset:192
	ds_read2st64_b32 v[26:27], v64 offset0:8 offset1:9
	v_add_u32_e32 v206, s99, v16
	v_mul_hi_u32 v207, v206, s101
	v_mul_u32_u24_e32 v207, 0x5700, v207
	v_sub_u32_e32 v206, v206, v207
	v_add_u32_e32 v206, s100, v206
	ds_read_u16 v32, v206 offset:128
	v_add_u32_e32 v206, s99, v16
	v_mul_hi_u32 v207, v206, s101
	v_mul_u32_u24_e32 v207, 0x5700, v207
	v_sub_u32_e32 v206, v206, v207
	v_add_u32_e32 v206, s100, v206
	ds_read_u16 v33, v206 offset:192
	v_lshlrev_b32_e32 v16, 16, v95
	v_mul_f32_e32 v16, v18, v16
	v_bfe_u32 v17, v16, 16, 1
	v_add3_u32 v16, v16, v17, s61
	v_mad_i64_i32 v[28:29], s[4:5], v39, s62, v[4:5]
	v_add_u32_e32 v39, 8, v36
	global_store_short_d16_hi v[28:29], v16, off
	v_mad_i64_i32 v[16:17], s[4:5], v39, s57, v[6:7]
	v_lshl_add_u64 v[16:17], v[16:17], 0, s[0:1]
	v_lshl_add_u64 v[30:31], v[16:17], 0, v[2:3]
	v_add_co_u32_e32 v16, vcc, s60, v30
	s_nop 1
	v_mov_b32_dpp v22, v14 row_mirror row_mask:0xf bank_mask:0xf
	s_nop 0
	v_addc_co_u32_e32 v17, vcc, 0, v31, vcc
	v_add_u32_e32 v206, s98, v16
	v_mul_hi_u32 v207, v206, s101
	v_mul_u32_u24_e32 v207, 0x5700, v207
	v_sub_u32_e32 v206, v206, v207
	v_add_u32_e32 v206, s100, v206
	ds_read_u16 v93, v206
	s_waitcnt lgkmcnt(1)
	v_sub_f32_e32 v26, v78, v26
	s_waitcnt lgkmcnt(0)
	v_add_f32_e32 v14, v14, v22
	ds_bpermute_b32 v22, v209, v14
	v_sub_f32_e32 v78, v79, v15
	v_sub_f32_e32 v79, v80, v21
	v_mul_f32_e32 v15, v78, v78
	v_sub_f32_e32 v80, v81, v23
	s_waitcnt lgkmcnt(0)
	v_add_f32_e32 v14, v14, v22
	v_fmamk_f32 v14, v14, 0x3c000000, v211
	v_mul_f32_e32 v21, 0x4f800000, v14
	v_cmp_gt_f32_e32 vcc, s58, v14
	v_fmac_f32_e32 v15, v83, v83
	v_fmac_f32_e32 v15, v79, v79
	v_cndmask_b32_e32 v14, v14, v21, vcc
	v_sqrt_f32_e32 v21, v14
	v_fmac_f32_e32 v15, v80, v80
	v_sub_f32_e32 v94, v77, v10
	ds_read2st64_b32 v[24:25], v64 offset0:10 offset1:11
	ds_read2st64_b32 v[18:19], v64 offset0:12 offset1:13
	ds_read2st64_b32 v[16:17], v64 offset0:14 offset1:15
	v_add_u32_e32 v22, -1, v21
	v_fma_f32 v23, -v22, v21, v14
	v_cmp_ge_f32_e64 s[4:5], 0, v23
	v_add_u32_e32 v23, 1, v21
	v_mul_f32_e32 v10, v94, v94
	v_cndmask_b32_e64 v22, v21, v22, s[4:5]
	v_fma_f32 v21, -v23, v21, v14
	v_cmp_lt_f32_e64 s[4:5], 0, v21
	v_fmac_f32_e32 v10, v84, v84
	v_sub_f32_e32 v70, v70, v27
	v_cndmask_b32_e64 v21, v22, v23, s[4:5]
	s_nop 1
	v_mov_b32_dpp v23, v15 quad_perm:[1,0,3,2] row_mask:0xf bank_mask:0xf
	v_mul_f32_e32 v22, 0x37800000, v21
	v_cndmask_b32_e32 v21, v21, v22, vcc
	v_cmp_class_f32_e32 vcc, v14, v212
	s_waitcnt lgkmcnt(3)
	v_sub_f32_e32 v24, v69, v24
	s_waitcnt lgkmcnt(0)
	v_add_f32_e32 v15, v15, v23
	v_cndmask_b32_e32 v14, v21, v14, vcc
	v_div_scale_f32 v21, s[4:5], v14, v14, s59
	v_rcp_f32_e32 v22, v21
	s_nop 1
	v_mov_b32_dpp v23, v15 quad_perm:[2,3,0,1] row_mask:0xf bank_mask:0xf
	v_sub_f32_e32 v18, v67, v18
	v_sub_f32_e32 v16, v44, v16
	v_fma_f32 v77, -v21, v22, 1.0
	v_fmac_f32_e32 v22, v77, v22
	v_div_scale_f32 v77, vcc, s59, v14, s59
	s_waitcnt lgkmcnt(0)
	v_add_f32_e32 v15, v15, v23
	v_mul_f32_e32 v81, v77, v22
	s_nop 1
	v_mov_b32_dpp v23, v15 row_half_mirror row_mask:0xf bank_mask:0xf
	v_fma_f32 v95, -v21, v81, v77
	v_fmac_f32_e32 v81, v95, v22
	v_fma_f32 v21, -v21, v81, v77
	v_div_fmas_f32 v21, v21, v22, v81
	v_mul_f32_e32 v22, v90, v20
	s_waitcnt lgkmcnt(0)
	v_add_f32_e32 v81, v15, v23
	v_mul_f32_e32 v22, v22, v35
	v_lshlrev_b32_e32 v23, 16, v89
	v_mul_f32_e32 v22, v22, v23
	v_bfe_u32 v23, v22, 16, 1
	v_add3_u32 v22, v22, v23, s61
	global_store_short_d16_hi v[28:29], v22, off offset:64
	v_mul_f32_e32 v22, v91, v20
	v_div_fixup_f32 v77, v21, v14, s59
	v_mul_f32_e32 v22, v22, v37
	v_lshlrev_b32_e32 v23, 16, v32
	v_mul_f32_e32 v14, v88, v77
	v_mul_f32_e32 v22, v22, v23
	v_mul_f32_e32 v21, v14, v34
	v_lshl_add_u64 v[14:15], v[30:31], 0, s[20:21]
	v_bfe_u32 v23, v22, 16, 1
	v_add_u32_e32 v206, s99, v14
	v_mul_hi_u32 v207, v206, s101
	v_mul_u32_u24_e32 v207, 0x5700, v207
	v_sub_u32_e32 v206, v206, v207
	v_add_u32_e32 v206, s100, v206
	ds_read_u16 v30, v206 offset:64
	v_add3_u32 v22, v22, v23, s61
	v_mul_f32_e32 v20, v92, v20
	global_store_short_d16_hi v[28:29], v22, off offset:128
	v_mul_f32_e32 v20, v20, v38
	v_lshlrev_b32_e32 v22, 16, v33
	v_mul_f32_e32 v20, v20, v22
	v_bfe_u32 v22, v20, 16, 1
	v_add3_u32 v20, v20, v22, s61
	global_store_short_d16_hi v[28:29], v20, off offset:192
	v_add_u32_e32 v206, s99, v14
	v_mul_hi_u32 v207, v206, s101
	v_mul_u32_u24_e32 v207, 0x5700, v207
	v_sub_u32_e32 v206, v206, v207
	v_add_u32_e32 v206, s100, v206
	ds_read_u16 v28, v206 offset:128
	s_nop 0
	v_add_u32_e32 v206, s99, v14
	v_mul_hi_u32 v207, v206, s101
	v_mul_u32_u24_e32 v207, 0x5700, v207
	v_sub_u32_e32 v206, v206, v207
	v_add_u32_e32 v206, s100, v206
	ds_read_u16 v29, v206 offset:192
	v_lshlrev_b32_e32 v14, 16, v93
	v_mul_f32_e32 v14, v21, v14
	v_bfe_u32 v15, v14, 16, 1
	v_add3_u32 v20, v14, v15, s61
	v_mad_i64_i32 v[14:15], s[4:5], v39, s62, v[4:5]
	v_add_u32_e32 v31, 9, v36
	s_nop 1
	v_mov_b32_dpp v95, v81 row_mirror row_mask:0xf bank_mask:0xf
	global_store_short_d16_hi v[14:15], v20, off
	v_mad_i64_i32 v[20:21], s[4:5], v31, s57, v[6:7]
	v_lshl_add_u64 v[20:21], v[20:21], 0, s[0:1]
	v_lshl_add_u64 v[20:21], v[20:21], 0, v[2:3]
	v_add_co_u32_e32 v22, vcc, s60, v20
	v_sub_f32_e32 v88, v75, v8
	s_nop 0
	v_addc_co_u32_e32 v23, vcc, 0, v21, vcc
	v_add_u32_e32 v206, s98, v22
	v_mul_hi_u32 v207, v206, s101
	v_mul_u32_u24_e32 v207, 0x5700, v207
	v_sub_u32_e32 v206, v206, v207
	v_add_u32_e32 v206, s100, v206
	ds_read_u16 v22, v206
	s_waitcnt lgkmcnt(0)
; DI float bf2f(unsigned short u) { return __uint_as_float((unsigned)u << 16); }
; DI unsigned f2bf(float f) { unsigned u = __float_as_uint(f); return (u + 0x7fffu + ((u >> 16) & 1u)) >> 16; }
; DI int crow(int i, int hh) { return (i & 3) + 8 * (i >> 2) + 4 * hh; }
; DI void attn_unit(Ctx A_, LAS unsigned char* lds, int b, int h, int qb, float lam, int wave, int lane) {
;     ...
;     if (mp == 0) {
;         float ssq[16];
; #pragma unroll
;         for (int i = 0; i < 16; ++i) ssq[i] = 0.f;
; #pragma unroll
;         for (int nb = 0; nb < 4; ++nb)
; #pragma unroll
;             for (int i = 0; i < 16; ++i) { const float d = o[nb][i] - X2[(nb * 16 + i) * 64]; o[nb][i] = d; ssq[i] += d * d; }
; #pragma unroll
;         for (int i = 0; i < 16; ++i) {
;             float v = ssq[i];
; #pragma unroll
;             for (int x = 1; x < 32; x <<= 1) v += __shfl_xor(v, x);
;             ssq[i] = ONE_M_LAMINIT / sqrtf(v * (1.0f / 128.0f) + NORM_EPS);
;         }
; #pragma unroll
;         for (int nb = 0; nb < 4; ++nb) {
;             const float sn = SUB_NORM[nb * 32 + r_e];
; #pragma unroll
;             for (int i = 0; i < 16; ++i) {
;                 const size_t rw = (size_t)(rowq_e + crow(i, hh_e));
;                 Y_[rw * YLD + C_YA + h_e * 128 + nb * 32 + r_e] = (bf16)f2bf(o[nb][i] * ssq[i] * sn * bf2f(P[rw * PLD + C_ZA + h_e * 128 + nb * 32 + r_e]));
;             }
;         }
;     }
	v_add_f32_e32 v23, v81, v95
	ds_bpermute_b32 v32, v209, v23
	v_sub_f32_e32 v39, v74, v11
	v_sub_f32_e32 v89, v76, v12
	v_fmac_f32_e32 v10, v88, v88
	v_fmac_f32_e32 v10, v89, v89
	s_waitcnt lgkmcnt(0)
	v_add_f32_e32 v8, v23, v32
	v_fmamk_f32 v8, v8, 0x3c000000, v211
	v_mul_f32_e32 v11, 0x4f800000, v8
	v_cmp_gt_f32_e32 vcc, s58, v8
	ds_read2st64_b32 v[74:75], v64 offset0:24 offset1:25
	v_mul_f32_e32 v33, v39, v39
	v_cndmask_b32_e32 v8, v8, v11, vcc
	v_sqrt_f32_e32 v11, v8
	v_fmac_f32_e32 v33, v82, v82
	s_waitcnt lgkmcnt(0)
	v_sub_f32_e32 v74, v72, v74
	v_add_u32_e32 v92, 11, v36
	v_add_u32_e32 v12, -1, v11
	v_fma_f32 v23, -v12, v11, v8
	v_cmp_ge_f32_e64 s[4:5], 0, v23
	v_add_u32_e32 v23, 1, v11
	v_sub_f32_e32 v71, v71, v75
	v_cndmask_b32_e64 v12, v11, v12, s[4:5]
	v_fma_f32 v11, -v23, v11, v8
	v_cmp_lt_f32_e64 s[4:5], 0, v11
	v_mul_f32_e32 v75, v71, v71
	v_fmac_f32_e32 v75, v70, v70
	v_cndmask_b32_e64 v11, v12, v23, s[4:5]
	v_mul_f32_e32 v12, 0x37800000, v11
	v_cndmask_b32_e32 v11, v11, v12, vcc
	s_nop 1
	v_mov_b32_dpp v12, v10 quad_perm:[1,0,3,2] row_mask:0xf bank_mask:0xf
	v_cmp_class_f32_e32 vcc, v8, v212
	v_sub_f32_e32 v17, v42, v17
	s_waitcnt lgkmcnt(0)
	v_add_f32_e32 v10, v10, v12
	s_nop 1
	v_mov_b32_dpp v12, v10 quad_perm:[2,3,0,1] row_mask:0xf bank_mask:0xf
	v_cndmask_b32_e32 v8, v11, v8, vcc
	v_div_scale_f32 v11, s[4:5], v8, v8, s59
	v_rcp_f32_e32 v23, v11
	s_waitcnt lgkmcnt(0)
	v_add_f32_e32 v10, v10, v12
	s_nop 1
	v_mov_b32_dpp v12, v10 row_half_mirror row_mask:0xf bank_mask:0xf
	v_fma_f32 v32, -v11, v23, 1.0
	v_fmac_f32_e32 v23, v32, v23
	v_div_scale_f32 v32, vcc, s59, v8, s59
	v_mul_f32_e32 v76, v32, v23
	s_waitcnt lgkmcnt(0)
	v_add_f32_e32 v10, v10, v12
	v_fma_f32 v81, -v11, v76, v32
	s_nop 1
	v_mov_b32_dpp v12, v10 row_mirror row_mask:0xf bank_mask:0xf
	v_fmac_f32_e32 v76, v81, v23
	v_fma_f32 v11, -v11, v76, v32
	v_div_fmas_f32 v11, v11, v23, v76
	v_div_fixup_f32 v32, v11, v8, s59
	s_waitcnt lgkmcnt(0)
	v_add_f32_e32 v8, v10, v12
	v_mul_f32_e32 v10, v83, v32
	v_mul_f32_e32 v23, v10, v34
	v_lshl_add_u64 v[10:11], v[20:21], 0, s[20:21]
	v_mul_f32_e32 v20, v85, v77
	v_mul_f32_e32 v20, v20, v35
	v_lshlrev_b32_e32 v21, 16, v30
	v_mul_f32_e32 v20, v20, v21
	v_bfe_u32 v21, v20, 16, 1
	v_add3_u32 v20, v20, v21, s61
	global_store_short_d16_hi v[14:15], v20, off offset:64
	v_mul_f32_e32 v20, v86, v77
	v_mul_f32_e32 v20, v20, v37
	v_lshlrev_b32_e32 v21, 16, v28
	v_mul_f32_e32 v20, v20, v21
	v_bfe_u32 v21, v20, 16, 1
	v_add3_u32 v20, v20, v21, s61
	v_add_u32_e32 v206, s99, v10
	v_mul_hi_u32 v207, v206, s101
	v_mul_u32_u24_e32 v207, 0x5700, v207
	v_sub_u32_e32 v206, v206, v207
	v_add_u32_e32 v206, s100, v206
	ds_read_u16 v30, v206 offset:64
	v_lshlrev_b32_e32 v21, 16, v29
	global_store_short_d16_hi v[14:15], v20, off offset:128
	v_mul_f32_e32 v20, v87, v77
	v_mul_f32_e32 v20, v20, v38
	v_mul_f32_e32 v20, v20, v21
	v_bfe_u32 v21, v20, 16, 1
	v_add3_u32 v20, v20, v21, s61
	global_store_short_d16_hi v[14:15], v20, off offset:192
	v_add_u32_e32 v206, s99, v10
	v_mul_hi_u32 v207, v206, s101
	v_mul_u32_u24_e32 v207, 0x5700, v207
	v_sub_u32_e32 v206, v206, v207
	v_add_u32_e32 v206, s100, v206
	ds_read_u16 v76, v206 offset:128
	v_add_u32_e32 v206, s99, v10
	v_mul_hi_u32 v207, v206, s101
	v_mul_u32_u24_e32 v207, 0x5700, v207
	v_sub_u32_e32 v206, v206, v207
	v_add_u32_e32 v206, s100, v206
	ds_read_u16 v77, v206 offset:192
	v_lshlrev_b32_e32 v10, 16, v22
	v_mul_f32_e32 v10, v23, v10
	v_bfe_u32 v11, v10, 16, 1
	v_add3_u32 v10, v10, v11, s61
	v_mad_i64_i32 v[20:21], s[4:5], v31, s62, v[4:5]
	v_add_u32_e32 v31, 10, v36
	ds_bpermute_b32 v12, v209, v8
	global_store_short_d16_hi v[20:21], v10, off
	v_mad_i64_i32 v[10:11], s[4:5], v31, s57, v[6:7]
	v_lshl_add_u64 v[10:11], v[10:11], 0, s[0:1]
	v_lshl_add_u64 v[22:23], v[10:11], 0, v[2:3]
	v_add_co_u32_e32 v10, vcc, s60, v22
	s_waitcnt lgkmcnt(0)
	v_add_f32_e32 v8, v8, v12
	v_addc_co_u32_e32 v11, vcc, 0, v23, vcc
	v_add_u32_e32 v206, s98, v10
	v_mul_hi_u32 v207, v206, s101
	v_mul_u32_u24_e32 v207, 0x5700, v207
	v_sub_u32_e32 v206, v206, v207
	v_add_u32_e32 v206, s100, v206
	ds_read_u16 v81, v206
	v_fmamk_f32 v8, v8, 0x3c000000, v211
	v_sub_f32_e32 v85, v65, v9
	v_mul_f32_e32 v9, 0x4f800000, v8
	v_cmp_gt_f32_e32 vcc, s58, v8
	v_sub_f32_e32 v86, v73, v13
	v_fmac_f32_e32 v33, v85, v85
	v_cndmask_b32_e32 v8, v8, v9, vcc
	v_sqrt_f32_e32 v9, v8
	v_fmac_f32_e32 v33, v86, v86
	ds_read2st64_b32 v[28:29], v64 offset0:26 offset1:27
	ds_read2st64_b32 v[14:15], v64 offset0:28 offset1:29
	ds_read2st64_b32 v[10:11], v64 offset0:30 offset1:31
	ds_read2st64_b32 v[72:73], v64 offset0:40 offset1:41
	v_add_u32_e32 v12, -1, v9
	v_fma_f32 v13, -v12, v9, v8
	v_cmp_ge_f32_e64 s[4:5], 0, v13
	v_add_u32_e32 v13, 1, v9
	s_waitcnt lgkmcnt(0)
	v_sub_f32_e32 v72, v62, v72
	v_cndmask_b32_e64 v12, v9, v12, s[4:5]
	v_fma_f32 v9, -v13, v9, v8
	v_cmp_lt_f32_e64 s[4:5], 0, v9
	v_mul_f32_e32 v83, v74, v74
	v_fmac_f32_e32 v83, v26, v26
	v_cndmask_b32_e64 v9, v12, v13, s[4:5]
	v_mul_f32_e32 v12, 0x37800000, v9
	v_cndmask_b32_e32 v9, v9, v12, vcc
	s_nop 1
	v_mov_b32_dpp v12, v33 quad_perm:[1,0,3,2] row_mask:0xf bank_mask:0xf
	v_cmp_class_f32_e32 vcc, v8, v212
	v_fmac_f32_e32 v83, v72, v72
	v_sub_f32_e32 v73, v60, v73
	v_cndmask_b32_e32 v8, v9, v8, vcc
	s_waitcnt lgkmcnt(0)
	v_add_f32_e32 v12, v33, v12
	s_nop 1
	v_mov_b32_dpp v33, v12 quad_perm:[2,3,0,1] row_mask:0xf bank_mask:0xf
	v_div_scale_f32 v9, s[4:5], v8, v8, s59
	v_rcp_f32_e32 v13, v9
	v_fmac_f32_e32 v75, v73, v73
	s_waitcnt lgkmcnt(0)
	v_add_f32_e32 v12, v12, v33
	s_nop 1
	v_mov_b32_dpp v33, v12 row_half_mirror row_mask:0xf bank_mask:0xf
	v_fma_f32 v65, -v9, v13, 1.0
	v_fmac_f32_e32 v13, v65, v13
	v_div_scale_f32 v65, vcc, s59, v8, s59
	v_mul_f32_e32 v87, v65, v13
	v_fma_f32 v90, -v9, v87, v65
	s_waitcnt lgkmcnt(0)
; DI float bf2f(unsigned short u) { return __uint_as_float((unsigned)u << 16); }
; DI unsigned f2bf(float f) { unsigned u = __float_as_uint(f); return (u + 0x7fffu + ((u >> 16) & 1u)) >> 16; }
; DI int crow(int i, int hh) { return (i & 3) + 8 * (i >> 2) + 4 * hh; }
; DI void attn_unit(Ctx A_, LAS unsigned char* lds, int b, int h, int qb, float lam, int wave, int lane) {
;     ...
;     if (mp == 0) {
;         float ssq[16];
; #pragma unroll
;         for (int i = 0; i < 16; ++i) ssq[i] = 0.f;
; #pragma unroll
;         for (int nb = 0; nb < 4; ++nb)
; #pragma unroll
;             for (int i = 0; i < 16; ++i) { const float d = o[nb][i] - X2[(nb * 16 + i) * 64]; o[nb][i] = d; ssq[i] += d * d; }
; #pragma unroll
;         for (int i = 0; i < 16; ++i) {
;             float v = ssq[i];
; #pragma unroll
;             for (int x = 1; x < 32; x <<= 1) v += __shfl_xor(v, x);
;             ssq[i] = ONE_M_LAMINIT / sqrtf(v * (1.0f / 128.0f) + NORM_EPS);
;         }
; #pragma unroll
;         for (int nb = 0; nb < 4; ++nb) {
;             const float sn = SUB_NORM[nb * 32 + r_e];
; #pragma unroll
;             for (int i = 0; i < 16; ++i) {
;                 const size_t rw = (size_t)(rowq_e + crow(i, hh_e));
;                 Y_[rw * YLD + C_YA + h_e * 128 + nb * 32 + r_e] = (bf16)f2bf(o[nb][i] * ssq[i] * sn * bf2f(P[rw * PLD + C_ZA + h_e * 128 + nb * 32 + r_e]));
;             }
;         }
;     }
	v_add_f32_e32 v12, v12, v33
	v_fmac_f32_e32 v87, v90, v13
	s_nop 1
	v_mov_b32_dpp v33, v12 row_mirror row_mask:0xf bank_mask:0xf
	v_fma_f32 v9, -v9, v87, v65
	v_div_fmas_f32 v9, v9, v13, v87
	v_div_fixup_f32 v65, v9, v8, s59
	v_mul_f32_e32 v8, v84, v65
	v_mul_f32_e32 v13, v78, v32
	s_waitcnt lgkmcnt(0)
	v_add_f32_e32 v33, v12, v33
	v_mul_f32_e32 v12, v8, v34
	v_lshl_add_u64 v[8:9], v[22:23], 0, s[20:21]
	v_mul_f32_e32 v13, v13, v35
	v_lshlrev_b32_e32 v22, 16, v30
	v_mul_f32_e32 v13, v13, v22
	v_bfe_u32 v22, v13, 16, 1
	v_add3_u32 v13, v13, v22, s61
	global_store_short_d16_hi v[20:21], v13, off offset:64
	v_mul_f32_e32 v13, v79, v32
	v_mul_f32_e32 v13, v13, v37
	v_lshlrev_b32_e32 v22, 16, v76
	v_mul_f32_e32 v13, v13, v22
	v_bfe_u32 v22, v13, 16, 1
	v_add3_u32 v13, v13, v22, s61
	global_store_short_d16_hi v[20:21], v13, off offset:128
	v_mul_f32_e32 v13, v80, v32
	v_add_u32_e32 v206, s99, v8
	v_mul_hi_u32 v207, v206, s101
	v_mul_u32_u24_e32 v207, 0x5700, v207
	v_sub_u32_e32 v206, v206, v207
	v_add_u32_e32 v206, s100, v206
	ds_read_u16 v84, v206 offset:64
	v_mul_f32_e32 v13, v13, v38
	v_lshlrev_b32_e32 v22, 16, v77
	v_mul_f32_e32 v13, v13, v22
	v_bfe_u32 v22, v13, 16, 1
	v_add3_u32 v13, v13, v22, s61
	global_store_short_d16_hi v[20:21], v13, off offset:192
	v_add_u32_e32 v206, s99, v8
	v_mul_hi_u32 v207, v206, s101
	v_mul_u32_u24_e32 v207, 0x5700, v207
	v_sub_u32_e32 v206, v206, v207
	v_add_u32_e32 v206, s100, v206
	ds_read_u16 v90, v206 offset:128
	v_add_u32_e32 v206, s99, v8
	v_mul_hi_u32 v207, v206, s101
	v_mul_u32_u24_e32 v207, 0x5700, v207
	v_sub_u32_e32 v206, v206, v207
	v_add_u32_e32 v206, s100, v206
	ds_read_u16 v91, v206 offset:192
	v_mad_i64_i32 v[76:77], s[4:5], v31, s62, v[4:5]
	ds_bpermute_b32 v87, v209, v33
	v_lshlrev_b32_e32 v8, 16, v81
	v_mul_f32_e32 v8, v12, v8
	v_bfe_u32 v9, v8, 16, 1
	v_add3_u32 v8, v8, v9, s61
	global_store_short_d16_hi v[76:77], v8, off
	v_mad_i64_i32 v[8:9], s[4:5], v92, s57, v[6:7]
	v_lshl_add_u64 v[8:9], v[8:9], 0, s[0:1]
	v_lshl_add_u64 v[78:79], v[8:9], 0, v[2:3]
	v_add_co_u32_e32 v8, vcc, s60, v78
	v_sub_f32_e32 v57, v57, v28
	s_nop 0
	v_addc_co_u32_e32 v9, vcc, 0, v79, vcc
	v_add_u32_e32 v206, s98, v8
	v_mul_hi_u32 v207, v206, s101
	v_mul_u32_u24_e32 v207, 0x5700, v207
	v_sub_u32_e32 v206, v206, v207
	v_add_u32_e32 v206, s100, v206
	ds_read_u16 v93, v206
	s_waitcnt lgkmcnt(0)
	v_add_f32_e32 v8, v33, v87
	v_fmamk_f32 v8, v8, 0x3c000000, v211
	v_mul_f32_e32 v9, 0x4f800000, v8
	v_cmp_gt_f32_e32 vcc, s58, v8
	ds_read2st64_b32 v[30:31], v64 offset0:42 offset1:43
	ds_read2st64_b32 v[20:21], v64 offset0:44 offset1:45
	ds_read2st64_b32 v[12:13], v64 offset0:46 offset1:47
	ds_read2st64_b32 v[80:81], v64 offset0:56 offset1:57
	v_cndmask_b32_e32 v62, v8, v9, vcc
	v_sqrt_f32_e32 v87, v62
	ds_read2st64_b32 v[32:33], v64 offset0:58 offset1:59
	ds_read2st64_b32 v[22:23], v64 offset0:60 offset1:61
	ds_read2st64_b32 v[8:9], v64 offset0:62 offset1:63
	s_waitcnt lgkmcnt(6)
	v_sub_f32_e32 v30, v58, v30
	s_waitcnt lgkmcnt(3)
	v_sub_f32_e32 v80, v63, v80
	v_add_u32_e32 v63, -1, v87
	v_fma_f32 v64, -v63, v87, v62
	v_cmp_ge_f32_e64 s[4:5], 0, v64
	v_add_u32_e32 v64, 1, v87
	v_fmac_f32_e32 v83, v80, v80
	v_cndmask_b32_e64 v63, v87, v63, s[4:5]
	v_fma_f32 v87, -v64, v87, v62
	v_cmp_lt_f32_e64 s[4:5], 0, v87
	s_nop 1
	v_mov_b32_dpp v87, v83 quad_perm:[1,0,3,2] row_mask:0xf bank_mask:0xf
	s_waitcnt lgkmcnt(3)
	v_sub_f32_e32 v32, v59, v32
	v_cndmask_b32_e64 v63, v63, v64, s[4:5]
	v_mul_f32_e32 v64, 0x37800000, v63
	v_cndmask_b32_e32 v63, v63, v64, vcc
	v_cmp_class_f32_e32 vcc, v62, v212
	s_waitcnt lgkmcnt(0)
	v_add_f32_e32 v83, v83, v87
	s_nop 1
	v_mov_b32_dpp v87, v83 quad_perm:[2,3,0,1] row_mask:0xf bank_mask:0xf
	v_cndmask_b32_e32 v62, v63, v62, vcc
	v_div_scale_f32 v63, s[4:5], v62, v62, s59
	v_rcp_f32_e32 v64, v63
	s_waitcnt lgkmcnt(0)
	v_add_f32_e32 v83, v83, v87
	s_nop 1
	v_mov_b32_dpp v87, v83 row_half_mirror row_mask:0xf bank_mask:0xf
	v_mul_f32_e32 v28, v57, v57
	v_fma_f32 v95, -v63, v64, 1.0
	v_fmac_f32_e32 v64, v95, v64
	v_div_scale_f32 v95, vcc, s59, v62, s59
	v_mul_f32_e32 v96, v95, v64
	v_fma_f32 v97, -v63, v96, v95
	v_fmac_f32_e32 v96, v97, v64
	v_fma_f32 v63, -v63, v96, v95
	v_div_fmas_f32 v63, v63, v64, v96
	v_div_fixup_f32 v95, v63, v62, s59
	v_mul_f32_e32 v62, v82, v95
	v_mul_f32_e32 v64, v62, v34
	v_lshl_add_u64 v[62:63], v[78:79], 0, s[20:21]
	v_mul_f32_e32 v78, v94, v65
	v_mul_f32_e32 v78, v78, v35
	s_waitcnt lgkmcnt(0)
	v_add_f32_e32 v83, v83, v87
	s_nop 1
	v_mov_b32_dpp v87, v83 row_mirror row_mask:0xf bank_mask:0xf
	v_mul_f32_e32 v39, v39, v95
	v_mul_f32_e32 v39, v39, v35
	v_fmac_f32_e32 v28, v24, v24
	v_lshlrev_b32_e32 v79, 16, v84
	v_mul_f32_e32 v78, v78, v79
	v_bfe_u32 v79, v78, 16, 1
	v_add3_u32 v78, v78, v79, s61
	v_mul_f32_e32 v79, v88, v65
	v_mul_f32_e32 v79, v79, v37
	v_lshlrev_b32_e32 v82, 16, v90
	v_mul_f32_e32 v79, v79, v82
	v_bfe_u32 v82, v79, 16, 1
	global_store_short_d16_hi v[76:77], v78, off offset:64
	v_add3_u32 v79, v79, v82, s61
	v_mul_f32_e32 v65, v89, v65
	v_add_u32_e32 v206, s99, v62
	v_mul_hi_u32 v207, v206, s101
	v_mul_u32_u24_e32 v207, 0x5700, v207
	v_sub_u32_e32 v206, v206, v207
	v_add_u32_e32 v206, s100, v206
	ds_read_u16 v78, v206 offset:64
	v_mul_f32_e32 v65, v65, v38
	global_store_short_d16_hi v[76:77], v79, off offset:128
	v_lshlrev_b32_e32 v79, 16, v91
	v_mul_f32_e32 v65, v65, v79
	v_bfe_u32 v79, v65, 16, 1
	v_add3_u32 v65, v65, v79, s61
	global_store_short_d16_hi v[76:77], v65, off offset:192
	v_add_u32_e32 v206, s99, v62
	v_mul_hi_u32 v207, v206, s101
	v_mul_u32_u24_e32 v207, 0x5700, v207
	v_sub_u32_e32 v206, v206, v207
	v_add_u32_e32 v206, s100, v206
	ds_read_u16 v79, v206 offset:128
	v_add_u32_e32 v206, s99, v62
	v_mul_hi_u32 v207, v206, s101
	v_mul_u32_u24_e32 v207, 0x5700, v207
	v_sub_u32_e32 v206, v206, v207
	v_add_u32_e32 v206, s100, v206
	ds_read_u16 v82, v206 offset:192
	v_add_u32_e32 v84, 16, v36
	s_waitcnt lgkmcnt(0)
; DI float bf2f(unsigned short u) { return __uint_as_float((unsigned)u << 16); }
; DI unsigned f2bf(float f) { unsigned u = __float_as_uint(f); return (u + 0x7fffu + ((u >> 16) & 1u)) >> 16; }
; DI int crow(int i, int hh) { return (i & 3) + 8 * (i >> 2) + 4 * hh; }
; DI void attn_unit(Ctx A_, LAS unsigned char* lds, int b, int h, int qb, float lam, int wave, int lane) {
;     ...
;     if (mp == 0) {
;         float ssq[16];
; #pragma unroll
;         for (int i = 0; i < 16; ++i) ssq[i] = 0.f;
; #pragma unroll
;         for (int nb = 0; nb < 4; ++nb)
; #pragma unroll
;             for (int i = 0; i < 16; ++i) { const float d = o[nb][i] - X2[(nb * 16 + i) * 64]; o[nb][i] = d; ssq[i] += d * d; }
; #pragma unroll
;         for (int i = 0; i < 16; ++i) {
;             float v = ssq[i];
; #pragma unroll
;             for (int x = 1; x < 32; x <<= 1) v += __shfl_xor(v, x);
;             ssq[i] = ONE_M_LAMINIT / sqrtf(v * (1.0f / 128.0f) + NORM_EPS);
;         }
; #pragma unroll
;         for (int nb = 0; nb < 4; ++nb) {
;             const float sn = SUB_NORM[nb * 32 + r_e];
; #pragma unroll
;             for (int i = 0; i < 16; ++i) {
;                 const size_t rw = (size_t)(rowq_e + crow(i, hh_e));
;                 Y_[rw * YLD + C_YA + h_e * 128 + nb * 32 + r_e] = (bf16)f2bf(o[nb][i] * ssq[i] * sn * bf2f(P[rw * PLD + C_ZA + h_e * 128 + nb * 32 + r_e]));
;             }
;         }
;     }
	v_add_f32_e32 v27, v83, v87
	v_fmac_f32_e32 v28, v30, v30
	v_fmac_f32_e32 v28, v32, v32
	v_lshlrev_b32_e32 v62, 16, v93
	v_mul_f32_e32 v62, v64, v62
	v_bfe_u32 v63, v62, 16, 1
	v_add3_u32 v64, v62, v63, s61
	v_mad_i64_i32 v[62:63], s[4:5], v92, s62, v[4:5]
	global_store_short_d16_hi v[62:63], v64, off
	v_mad_i64_i32 v[64:65], s[4:5], v84, s57, v[6:7]
	v_lshl_add_u64 v[64:65], v[64:65], 0, s[0:1]
	v_lshl_add_u64 v[64:65], v[64:65], 0, v[2:3]
	v_add_co_u32_e32 v76, vcc, s60, v64
	v_sub_f32_e32 v54, v54, v29
	s_nop 0
	v_addc_co_u32_e32 v77, vcc, 0, v65, vcc
	v_add_u32_e32 v206, s98, v76
	v_mul_hi_u32 v207, v206, s101
	v_mul_u32_u24_e32 v207, 0x5700, v207
	v_sub_u32_e32 v206, v206, v207
	v_add_u32_e32 v206, s100, v206
	ds_read_u16 v76, v206
	ds_bpermute_b32 v77, v209, v27
	v_sub_f32_e32 v31, v55, v31
	v_mul_f32_e32 v29, v54, v54
	v_sub_f32_e32 v33, v56, v33
	v_sub_f32_e32 v51, v51, v14
	s_waitcnt lgkmcnt(0)
	v_add_f32_e32 v27, v27, v77
	v_fmamk_f32 v27, v27, 0x3c000000, v211
	v_mul_f32_e32 v60, 0x4f800000, v27
	v_cmp_gt_f32_e32 vcc, s58, v27
	v_sub_f32_e32 v77, v61, v81
	v_fmac_f32_e32 v75, v77, v77
	v_cndmask_b32_e32 v27, v27, v60, vcc
	v_sqrt_f32_e32 v60, v27
	v_sub_f32_e32 v52, v52, v20
	v_sub_f32_e32 v22, v53, v22
	v_sub_f32_e32 v48, v48, v15
	v_add_u32_e32 v61, -1, v60
	v_fma_f32 v81, -v61, v60, v27
	v_cmp_ge_f32_e64 s[4:5], 0, v81
	v_add_u32_e32 v81, 1, v60
	v_sub_f32_e32 v49, v49, v21
	v_cndmask_b32_e64 v61, v60, v61, s[4:5]
	v_fma_f32 v60, -v81, v60, v27
	v_cmp_lt_f32_e64 s[4:5], 0, v60
	v_sub_f32_e32 v23, v50, v23
	v_sub_f32_e32 v12, v46, v12
	v_cndmask_b32_e64 v60, v61, v81, s[4:5]
	v_mul_f32_e32 v61, 0x37800000, v60
	v_cndmask_b32_e32 v60, v60, v61, vcc
	v_cmp_class_f32_e32 vcc, v27, v212
	s_nop 1
	v_mov_b32_dpp v81, v75 quad_perm:[1,0,3,2] row_mask:0xf bank_mask:0xf
	v_sub_f32_e32 v13, v40, v13
	v_cndmask_b32_e32 v27, v60, v27, vcc
	v_div_scale_f32 v60, s[4:5], v27, v27, s59
	v_rcp_f32_e32 v61, v60
	s_waitcnt lgkmcnt(0)
	v_add_f32_e32 v75, v75, v81
	s_nop 1
	v_mov_b32_dpp v81, v75 quad_perm:[2,3,0,1] row_mask:0xf bank_mask:0xf
	v_fma_f32 v83, -v60, v61, 1.0
	v_fmac_f32_e32 v61, v83, v61
	v_div_scale_f32 v83, vcc, s59, v27, s59
	v_mul_f32_e32 v87, v83, v61
	v_fma_f32 v88, -v60, v87, v83
	v_fmac_f32_e32 v87, v88, v61
	v_fma_f32 v60, -v60, v87, v83
	v_div_fmas_f32 v60, v60, v61, v87
	v_div_fixup_f32 v83, v60, v27, s59
	v_mul_f32_e32 v26, v26, v83
	v_lshlrev_b32_e32 v61, 16, v78
	v_mul_f32_e32 v39, v39, v61
	v_bfe_u32 v61, v39, 16, 1
	v_add3_u32 v39, v39, v61, s61
	v_mul_f32_e32 v61, v85, v95
	v_mul_f32_e32 v60, v26, v34
	v_lshl_add_u64 v[26:27], v[64:65], 0, s[20:21]
	v_mul_f32_e32 v61, v61, v37
	v_lshlrev_b32_e32 v64, 16, v79
	v_mul_f32_e32 v61, v61, v64
	v_bfe_u32 v64, v61, 16, 1
	v_add3_u32 v61, v61, v64, s61
	global_store_short_d16_hi v[62:63], v39, off offset:64
	global_store_short_d16_hi v[62:63], v61, off offset:128
	v_mul_f32_e32 v61, v86, v95
	v_add_u32_e32 v206, s99, v26
	v_mul_hi_u32 v207, v206, s101
	v_mul_u32_u24_e32 v207, 0x5700, v207
	v_sub_u32_e32 v206, v206, v207
	v_add_u32_e32 v206, s100, v206
	ds_read_u16 v39, v206 offset:64
	v_mul_f32_e32 v61, v61, v38
	v_lshlrev_b32_e32 v64, 16, v82
	v_mul_f32_e32 v61, v61, v64
	v_bfe_u32 v64, v61, 16, 1
	v_add3_u32 v61, v61, v64, s61
	global_store_short_d16_hi v[62:63], v61, off offset:192
	v_add_u32_e32 v206, s99, v26
	v_mul_hi_u32 v207, v206, s101
	v_mul_u32_u24_e32 v207, 0x5700, v207
	v_sub_u32_e32 v206, v206, v207
	v_add_u32_e32 v206, s100, v206
	ds_read_u16 v64, v206 offset:128
	v_add_u32_e32 v206, s99, v26
	v_mul_hi_u32 v207, v206, s101
	v_mul_u32_u24_e32 v207, 0x5700, v207
	v_sub_u32_e32 v206, v206, v207
	v_add_u32_e32 v206, s100, v206
	ds_read_u16 v65, v206 offset:192
	s_waitcnt lgkmcnt(0)
	v_add_f32_e32 v75, v75, v81
	s_nop 1
	v_mov_b32_dpp v81, v75 row_half_mirror row_mask:0xf bank_mask:0xf
	v_lshlrev_b32_e32 v26, 16, v76
	v_mul_f32_e32 v26, v60, v26
	v_bfe_u32 v27, v26, 16, 1
	s_waitcnt lgkmcnt(0)
	v_add_f32_e32 v75, v75, v81
	v_add3_u32 v60, v26, v27, s61
	v_mad_i64_i32 v[26:27], s[4:5], v84, s62, v[4:5]
	v_add_u32_e32 v76, 17, v36
	s_nop 1
	v_mov_b32_dpp v81, v75 row_mirror row_mask:0xf bank_mask:0xf
	global_store_short_d16_hi v[26:27], v60, off
	v_mad_i64_i32 v[60:61], s[4:5], v76, s57, v[6:7]
	v_lshl_add_u64 v[60:61], v[60:61], 0, s[0:1]
	v_lshl_add_u64 v[60:61], v[60:61], 0, v[2:3]
	v_add_co_u32_e32 v62, vcc, s60, v60
	v_lshlrev_b32_e32 v39, 16, v39
	v_addc_co_u32_e32 v63, vcc, 0, v61, vcc
	v_add_u32_e32 v206, s98, v62
	v_mul_hi_u32 v207, v206, s101
	v_mul_u32_u24_e32 v207, 0x5700, v207
	v_sub_u32_e32 v206, v206, v207
	v_add_u32_e32 v206, s100, v206
	ds_read_u16 v62, v206
	s_waitcnt lgkmcnt(0)
	v_add_f32_e32 v63, v75, v81
	ds_bpermute_b32 v69, v209, v63
	s_waitcnt lgkmcnt(0)
	v_add_f32_e32 v58, v63, v69
	v_fmamk_f32 v58, v58, 0x3c000000, v211
	v_mul_f32_e32 v63, 0x4f800000, v58
	v_cmp_gt_f32_e32 vcc, s58, v58
	s_nop 1
	v_cndmask_b32_e32 v58, v58, v63, vcc
	v_sqrt_f32_e32 v63, v58
	s_nop 0
	v_add_u32_e32 v59, -1, v63
	v_fma_f32 v69, -v59, v63, v58
	v_cmp_ge_f32_e64 s[4:5], 0, v69
	v_add_u32_e32 v69, 1, v63
	s_nop 0
	v_cndmask_b32_e64 v59, v63, v59, s[4:5]
	v_fma_f32 v63, -v69, v63, v58
	v_cmp_lt_f32_e64 s[4:5], 0, v63
	s_nop 1
	v_cndmask_b32_e64 v59, v59, v69, s[4:5]
	v_mul_f32_e32 v63, 0x37800000, v59
	v_cndmask_b32_e32 v59, v59, v63, vcc
	v_cmp_class_f32_e32 vcc, v58, v212
	s_nop 1
	v_mov_b32_dpp v69, v28 quad_perm:[1,0,3,2] row_mask:0xf bank_mask:0xf
	s_waitcnt lgkmcnt(0)
; DI float bf2f(unsigned short u) { return __uint_as_float((unsigned)u << 16); }
; DI unsigned f2bf(float f) { unsigned u = __float_as_uint(f); return (u + 0x7fffu + ((u >> 16) & 1u)) >> 16; }
; DI int crow(int i, int hh) { return (i & 3) + 8 * (i >> 2) + 4 * hh; }
; DI void attn_unit(Ctx A_, LAS unsigned char* lds, int b, int h, int qb, float lam, int wave, int lane) {
;     ...
;     if (mp == 0) {
;         float ssq[16];
; #pragma unroll
;         for (int i = 0; i < 16; ++i) ssq[i] = 0.f;
; #pragma unroll
;         for (int nb = 0; nb < 4; ++nb)
; #pragma unroll
;             for (int i = 0; i < 16; ++i) { const float d = o[nb][i] - X2[(nb * 16 + i) * 64]; o[nb][i] = d; ssq[i] += d * d; }
; #pragma unroll
;         for (int i = 0; i < 16; ++i) {
;             float v = ssq[i];
; #pragma unroll
;             for (int x = 1; x < 32; x <<= 1) v += __shfl_xor(v, x);
;             ssq[i] = ONE_M_LAMINIT / sqrtf(v * (1.0f / 128.0f) + NORM_EPS);
;         }
; #pragma unroll
;         for (int nb = 0; nb < 4; ++nb) {
;             const float sn = SUB_NORM[nb * 32 + r_e];
; #pragma unroll
;             for (int i = 0; i < 16; ++i) {
;                 const size_t rw = (size_t)(rowq_e + crow(i, hh_e));
;                 Y_[rw * YLD + C_YA + h_e * 128 + nb * 32 + r_e] = (bf16)f2bf(o[nb][i] * ssq[i] * sn * bf2f(P[rw * PLD + C_ZA + h_e * 128 + nb * 32 + r_e]));
;             }
;         }
;     }
	v_add_f32_e32 v28, v28, v69
	v_cndmask_b32_e32 v58, v59, v58, vcc
	v_div_scale_f32 v59, s[4:5], v58, v58, s59
	v_rcp_f32_e32 v63, v59
	s_nop 1
	v_mov_b32_dpp v69, v28 quad_perm:[2,3,0,1] row_mask:0xf bank_mask:0xf
	v_fma_f32 v75, -v59, v63, 1.0
	v_fmac_f32_e32 v63, v75, v63
	v_div_scale_f32 v75, vcc, s59, v58, s59
	v_mul_f32_e32 v78, v75, v63
	v_fma_f32 v79, -v59, v78, v75
	v_fmac_f32_e32 v78, v79, v63
	v_fma_f32 v59, -v59, v78, v75
	v_div_fmas_f32 v59, v59, v63, v78
	v_div_fixup_f32 v63, v59, v58, s59
	v_mul_f32_e32 v58, v70, v63
	v_mul_f32_e32 v70, v58, v34
	v_lshl_add_u64 v[58:59], v[60:61], 0, s[20:21]
	v_mul_f32_e32 v60, v74, v83
	v_mul_f32_e32 v60, v60, v35
	v_mul_f32_e32 v39, v60, v39
	v_bfe_u32 v60, v39, 16, 1
	v_add3_u32 v39, v39, v60, s61
	v_mul_f32_e32 v60, v72, v83
	v_mul_f32_e32 v60, v60, v37
	v_lshlrev_b32_e32 v61, 16, v64
	v_mul_f32_e32 v60, v60, v61
	v_bfe_u32 v61, v60, 16, 1
	global_store_short_d16_hi v[26:27], v39, off offset:64
	v_add3_u32 v60, v60, v61, s61
	v_add_u32_e32 v206, s99, v58
	v_mul_hi_u32 v207, v206, s101
	v_mul_u32_u24_e32 v207, 0x5700, v207
	v_sub_u32_e32 v206, v206, v207
	v_add_u32_e32 v206, s100, v206
	ds_read_u16 v39, v206 offset:64
	v_lshlrev_b32_e32 v61, 16, v65
	global_store_short_d16_hi v[26:27], v60, off offset:128
	v_mul_f32_e32 v60, v80, v83
	v_mul_f32_e32 v60, v60, v38
	v_mul_f32_e32 v60, v60, v61
	v_bfe_u32 v61, v60, 16, 1
	v_add3_u32 v60, v60, v61, s61
	global_store_short_d16_hi v[26:27], v60, off offset:192
	v_add_u32_e32 v206, s99, v58
	v_mul_hi_u32 v207, v206, s101
	v_mul_u32_u24_e32 v207, 0x5700, v207
	v_sub_u32_e32 v206, v206, v207
	v_add_u32_e32 v206, s100, v206
	ds_read_u16 v64, v206 offset:128
	v_add_u32_e32 v206, s99, v58
	v_mul_hi_u32 v207, v206, s101
	v_mul_u32_u24_e32 v207, 0x5700, v207
	v_sub_u32_e32 v206, v206, v207
	v_add_u32_e32 v206, s100, v206
	ds_read_u16 v65, v206 offset:192
	s_waitcnt lgkmcnt(0)
	v_add_f32_e32 v28, v28, v69
	s_nop 1
	v_mov_b32_dpp v69, v28 row_half_mirror row_mask:0xf bank_mask:0xf
	v_lshlrev_b32_e32 v26, 16, v62
	v_mul_f32_e32 v26, v70, v26
	v_bfe_u32 v27, v26, 16, 1
	v_add3_u32 v58, v26, v27, s61
	s_waitcnt lgkmcnt(0)
	v_add_f32_e32 v28, v28, v69
	v_mad_i64_i32 v[26:27], s[4:5], v76, s62, v[4:5]
	v_add_u32_e32 v62, 18, v36
	s_nop 1
	v_mov_b32_dpp v69, v28 row_mirror row_mask:0xf bank_mask:0xf
	global_store_short_d16_hi v[26:27], v58, off
	v_mad_i64_i32 v[58:59], s[4:5], v62, s57, v[6:7]
	v_lshl_add_u64 v[58:59], v[58:59], 0, s[0:1]
	v_lshl_add_u64 v[58:59], v[58:59], 0, v[2:3]
	v_add_co_u32_e32 v60, vcc, s60, v58
	v_lshlrev_b32_e32 v39, 16, v39
	v_addc_co_u32_e32 v61, vcc, 0, v59, vcc
	v_add_u32_e32 v206, s98, v60
	v_mul_hi_u32 v207, v206, s101
	v_mul_u32_u24_e32 v207, 0x5700, v207
	v_sub_u32_e32 v206, v206, v207
	v_add_u32_e32 v206, s100, v206
	ds_read_u16 v60, v206
	v_sub_f32_e32 v61, v68, v25
	s_waitcnt lgkmcnt(0)
	v_add_f32_e32 v25, v28, v69
	ds_bpermute_b32 v28, v209, v25
	v_fmac_f32_e32 v29, v61, v61
	v_fmac_f32_e32 v29, v31, v31
	v_fmac_f32_e32 v29, v33, v33
	s_waitcnt lgkmcnt(0)
	v_add_f32_e32 v25, v25, v28
	v_fmamk_f32 v25, v25, 0x3c000000, v211
	v_mul_f32_e32 v28, 0x4f800000, v25
	v_cmp_gt_f32_e32 vcc, s58, v25
	s_nop 1
	v_cndmask_b32_e32 v25, v25, v28, vcc
	v_sqrt_f32_e32 v28, v25
	s_nop 0
	v_add_u32_e32 v55, -1, v28
	v_fma_f32 v56, -v55, v28, v25
	v_cmp_ge_f32_e64 s[4:5], 0, v56
	v_add_u32_e32 v56, 1, v28
	s_nop 0
	v_cndmask_b32_e64 v55, v28, v55, s[4:5]
	v_fma_f32 v28, -v56, v28, v25
	v_cmp_lt_f32_e64 s[4:5], 0, v28
	s_nop 1
	v_cndmask_b32_e64 v28, v55, v56, s[4:5]
	s_nop 1
	v_mov_b32_dpp v56, v29 quad_perm:[1,0,3,2] row_mask:0xf bank_mask:0xf
	v_mul_f32_e32 v55, 0x37800000, v28
	v_cndmask_b32_e32 v28, v28, v55, vcc
	v_cmp_class_f32_e32 vcc, v25, v212
	s_waitcnt lgkmcnt(0)
	v_add_f32_e32 v29, v29, v56
	s_nop 1
	v_mov_b32_dpp v56, v29 quad_perm:[2,3,0,1] row_mask:0xf bank_mask:0xf
	v_cndmask_b32_e32 v25, v28, v25, vcc
	v_div_scale_f32 v28, s[4:5], v25, v25, s59
	v_rcp_f32_e32 v55, v28
	s_waitcnt lgkmcnt(0)
	v_add_f32_e32 v29, v29, v56
	s_nop 1
	v_mov_b32_dpp v56, v29 row_half_mirror row_mask:0xf bank_mask:0xf
	v_fma_f32 v68, -v28, v55, 1.0
	v_fmac_f32_e32 v55, v68, v55
	v_div_scale_f32 v68, vcc, s59, v25, s59
	v_mul_f32_e32 v69, v68, v55
	v_fma_f32 v70, -v28, v69, v68
	s_waitcnt lgkmcnt(0)
	v_add_f32_e32 v56, v29, v56
	v_mul_f32_e32 v29, v71, v63
	v_fmac_f32_e32 v69, v70, v55
	v_mul_f32_e32 v29, v29, v35
	v_fma_f32 v28, -v28, v69, v68
	v_mul_f32_e32 v29, v29, v39
	v_div_fmas_f32 v28, v28, v55, v69
	v_bfe_u32 v39, v29, 16, 1
	v_div_fixup_f32 v55, v28, v25, s59
	v_add3_u32 v29, v29, v39, s61
	v_mul_f32_e32 v24, v24, v55
	global_store_short_d16_hi v[26:27], v29, off offset:64
	v_mul_f32_e32 v29, v73, v63
	v_mul_f32_e32 v28, v24, v34
	v_lshl_add_u64 v[24:25], v[58:59], 0, s[20:21]
	v_mul_f32_e32 v29, v29, v37
	v_lshlrev_b32_e32 v58, 16, v64
	v_mul_f32_e32 v29, v29, v58
	v_bfe_u32 v58, v29, 16, 1
	v_add3_u32 v29, v29, v58, s61
	global_store_short_d16_hi v[26:27], v29, off offset:128
	v_mul_f32_e32 v29, v77, v63
	v_mul_f32_e32 v29, v29, v38
	v_lshlrev_b32_e32 v59, 16, v65
	v_mul_f32_e32 v29, v29, v59
	v_add_u32_e32 v206, s99, v24
	v_mul_hi_u32 v207, v206, s101
	v_mul_u32_u24_e32 v207, 0x5700, v207
	v_sub_u32_e32 v206, v206, v207
	v_add_u32_e32 v206, s100, v206
	ds_read_u16 v39, v206 offset:64
	v_add_u32_e32 v206, s99, v24
	v_mul_hi_u32 v207, v206, s101
	v_mul_u32_u24_e32 v207, 0x5700, v207
	v_sub_u32_e32 v206, v206, v207
	v_add_u32_e32 v206, s100, v206
	ds_read_u16 v58, v206 offset:128
	v_bfe_u32 v59, v29, 16, 1
	v_add3_u32 v29, v29, v59, s61
	global_store_short_d16_hi v[26:27], v29, off offset:192
	v_add_u32_e32 v206, s99, v24
	v_mul_hi_u32 v207, v206, s101
	v_mul_u32_u24_e32 v207, 0x5700, v207
	v_sub_u32_e32 v206, v206, v207
	v_add_u32_e32 v206, s100, v206
	ds_read_u16 v59, v206 offset:192
	v_lshlrev_b32_e32 v24, 16, v60
	v_mul_f32_e32 v24, v28, v24
	v_bfe_u32 v25, v24, 16, 1
	v_add3_u32 v26, v24, v25, s61
	v_mad_i64_i32 v[24:25], s[4:5], v62, s62, v[4:5]
	v_add_u32_e32 v60, 19, v36
	global_store_short_d16_hi v[24:25], v26, off
	v_mad_i64_i32 v[26:27], s[4:5], v60, s57, v[6:7]
	v_lshl_add_u64 v[26:27], v[26:27], 0, s[0:1]
	v_lshl_add_u64 v[26:27], v[26:27], 0, v[2:3]
	v_add_co_u32_e32 v28, vcc, s60, v26
	v_mul_f32_e32 v57, v57, v55
	s_nop 0
	v_addc_co_u32_e32 v29, vcc, 0, v27, vcc
	v_add_u32_e32 v206, s98, v28
	v_mul_hi_u32 v207, v206, s101
	v_mul_u32_u24_e32 v207, 0x5700, v207
	v_sub_u32_e32 v206, v206, v207
	v_add_u32_e32 v206, s100, v206
	ds_read_u16 v28, v206
	v_mul_f32_e32 v57, v57, v35
	v_mul_f32_e32 v30, v30, v55
	v_mul_f32_e32 v32, v32, v55
	s_nop 1
	v_mov_b32_dpp v68, v56 row_mirror row_mask:0xf bank_mask:0xf
	v_mul_f32_e32 v30, v30, v37
	v_mul_f32_e32 v32, v32, v38
	v_lshl_add_u64 v[26:27], v[26:27], 0, s[20:21]
	s_waitcnt lgkmcnt(3)
; DI float bf2f(unsigned short u) { return __uint_as_float((unsigned)u << 16); }
; DI unsigned f2bf(float f) { unsigned u = __float_as_uint(f); return (u + 0x7fffu + ((u >> 16) & 1u)) >> 16; }
; DI int crow(int i, int hh) { return (i & 3) + 8 * (i >> 2) + 4 * hh; }
; DI void attn_unit(Ctx A_, LAS unsigned char* lds, int b, int h, int qb, float lam, int wave, int lane) {
;     ...
;     if (mp == 0) {
;         float ssq[16];
; #pragma unroll
;         for (int i = 0; i < 16; ++i) ssq[i] = 0.f;
; #pragma unroll
;         for (int nb = 0; nb < 4; ++nb)
; #pragma unroll
;             for (int i = 0; i < 16; ++i) { const float d = o[nb][i] - X2[(nb * 16 + i) * 64]; o[nb][i] = d; ssq[i] += d * d; }
; #pragma unroll
;         for (int i = 0; i < 16; ++i) {
;             float v = ssq[i];
; #pragma unroll
;             for (int x = 1; x < 32; x <<= 1) v += __shfl_xor(v, x);
;             ssq[i] = ONE_M_LAMINIT / sqrtf(v * (1.0f / 128.0f) + NORM_EPS);
;         }
; #pragma unroll
;         for (int nb = 0; nb < 4; ++nb) {
;             const float sn = SUB_NORM[nb * 32 + r_e];
; #pragma unroll
;             for (int i = 0; i < 16; ++i) {
;                 const size_t rw = (size_t)(rowq_e + crow(i, hh_e));
;                 Y_[rw * YLD + C_YA + h_e * 128 + nb * 32 + r_e] = (bf16)f2bf(o[nb][i] * ssq[i] * sn * bf2f(P[rw * PLD + C_ZA + h_e * 128 + nb * 32 + r_e]));
;             }
;         }
;     }
	v_lshlrev_b32_e32 v39, 16, v39
	v_mul_f32_e32 v39, v57, v39
	v_bfe_u32 v57, v39, 16, 1
	v_add3_u32 v39, v39, v57, s61
	s_waitcnt lgkmcnt(2)
	v_lshlrev_b32_e32 v57, 16, v58
	s_waitcnt lgkmcnt(1)
	v_lshlrev_b32_e32 v55, 16, v59
	v_mul_f32_e32 v30, v30, v57
	v_mul_f32_e32 v32, v32, v55
	global_store_short_d16_hi v[24:25], v39, off offset:64
	v_bfe_u32 v57, v30, 16, 1
	v_bfe_u32 v55, v32, 16, 1
	v_add_u32_e32 v206, s99, v26
	v_mul_hi_u32 v207, v206, s101
	v_mul_u32_u24_e32 v207, 0x5700, v207
	v_sub_u32_e32 v206, v206, v207
	v_add_u32_e32 v206, s100, v206
	ds_read_u16 v39, v206 offset:64
	v_add3_u32 v30, v30, v57, s61
	v_add3_u32 v32, v32, v55, s61
	global_store_short_d16_hi v[24:25], v30, off offset:128
	global_store_short_d16_hi v[24:25], v32, off offset:192
	v_add_u32_e32 v206, s99, v26
	v_mul_hi_u32 v207, v206, s101
	v_mul_u32_u24_e32 v207, 0x5700, v207
	v_sub_u32_e32 v206, v206, v207
	v_add_u32_e32 v206, s100, v206
	ds_read_u16 v30, v206 offset:128
	v_add_u32_e32 v55, 24, v36
	v_add_u32_e32 v206, s99, v26
	v_mul_hi_u32 v207, v206, s101
	v_mul_u32_u24_e32 v207, 0x5700, v207
	v_sub_u32_e32 v206, v206, v207
	v_add_u32_e32 v206, s100, v206
	ds_read_u16 v32, v206 offset:192
	s_waitcnt lgkmcnt(0)
	v_add_f32_e32 v29, v56, v68
	ds_bpermute_b32 v56, v209, v29
	s_waitcnt lgkmcnt(0)
	v_add_f32_e32 v14, v29, v56
	v_fmamk_f32 v14, v14, 0x3c000000, v211
	v_mul_f32_e32 v29, 0x4f800000, v14
	v_cmp_gt_f32_e32 vcc, s58, v14
	v_mul_f32_e32 v56, v51, v51
	v_fmac_f32_e32 v56, v18, v18
	v_cndmask_b32_e32 v14, v14, v29, vcc
	v_sqrt_f32_e32 v29, v14
	v_fmac_f32_e32 v56, v52, v52
	v_fmac_f32_e32 v56, v22, v22
	v_add_u32_e32 v20, -1, v29
	v_fma_f32 v62, -v20, v29, v14
	v_cmp_ge_f32_e64 s[4:5], 0, v62
	v_add_u32_e32 v62, 1, v29
	v_lshlrev_b32_e32 v30, 16, v30
	v_cndmask_b32_e64 v20, v29, v20, s[4:5]
	v_fma_f32 v29, -v62, v29, v14
	v_cmp_lt_f32_e64 s[4:5], 0, v29
	s_nop 1
	v_cndmask_b32_e64 v20, v20, v62, s[4:5]
	v_mul_f32_e32 v29, 0x37800000, v20
	v_cndmask_b32_e32 v20, v20, v29, vcc
	v_cmp_class_f32_e32 vcc, v14, v212
	s_nop 1
	v_cndmask_b32_e32 v14, v20, v14, vcc
	v_div_scale_f32 v20, s[4:5], v14, v14, s59
	v_rcp_f32_e32 v29, v20
	v_div_scale_f32 v62, vcc, s59, v14, s59
	v_fma_f32 v53, -v20, v29, 1.0
	v_fmac_f32_e32 v29, v53, v29
	s_nop 1
	v_mov_b32_dpp v53, v56 quad_perm:[1,0,3,2] row_mask:0xf bank_mask:0xf
	v_mul_f32_e32 v63, v62, v29
	v_fma_f32 v64, -v20, v63, v62
	v_fmac_f32_e32 v63, v64, v29
	v_fma_f32 v20, -v20, v63, v62
	s_waitcnt lgkmcnt(0)
	v_add_f32_e32 v53, v56, v53
	s_nop 1
	v_mov_b32_dpp v56, v53 quad_perm:[2,3,0,1] row_mask:0xf bank_mask:0xf
	v_div_fmas_f32 v20, v20, v29, v63
	v_div_fixup_f32 v20, v20, v14, s59
	s_waitcnt lgkmcnt(0)
	v_add_f32_e32 v24, v53, v56
	s_nop 1
	v_mov_b32_dpp v25, v24 row_half_mirror row_mask:0xf bank_mask:0xf
	s_waitcnt lgkmcnt(0)
	v_add_f32_e32 v14, v24, v25
	v_mul_f32_e32 v24, v61, v20
	v_mul_f32_e32 v24, v24, v34
	v_lshlrev_b32_e32 v25, 16, v28
	v_mul_f32_e32 v24, v24, v25
	v_bfe_u32 v25, v24, 16, 1
	s_nop 1
	v_mov_b32_dpp v53, v14 row_mirror row_mask:0xf bank_mask:0xf
	v_add3_u32 v26, v24, v25, s61
	v_mad_i64_i32 v[24:25], s[4:5], v60, s62, v[4:5]
	global_store_short_d16_hi v[24:25], v26, off
	v_mad_i64_i32 v[26:27], s[4:5], v55, s57, v[6:7]
	v_lshl_add_u64 v[26:27], v[26:27], 0, s[0:1]
	v_lshl_add_u64 v[26:27], v[26:27], 0, v[2:3]
	v_add_co_u32_e32 v28, vcc, s60, v26
	s_waitcnt lgkmcnt(0)
	v_add_f32_e32 v14, v14, v53
	v_addc_co_u32_e32 v29, vcc, 0, v27, vcc
	v_add_u32_e32 v206, s98, v28
	v_mul_hi_u32 v207, v206, s101
	v_mul_u32_u24_e32 v207, 0x5700, v207
	v_sub_u32_e32 v206, v206, v207
	v_add_u32_e32 v206, s100, v206
	ds_read_u16 v28, v206
	v_sub_f32_e32 v29, v66, v19
	ds_bpermute_b32 v19, v209, v14
	v_mul_f32_e32 v53, v48, v48
	v_fmac_f32_e32 v53, v29, v29
	v_fmac_f32_e32 v53, v49, v49
	v_fmac_f32_e32 v53, v23, v23
	s_waitcnt lgkmcnt(0)
	v_add_f32_e32 v14, v14, v19
	v_fmamk_f32 v14, v14, 0x3c000000, v211
	v_mul_f32_e32 v15, 0x4f800000, v14
	v_cmp_gt_f32_e32 vcc, s58, v14
	s_nop 1
	v_mov_b32_dpp v56, v53 quad_perm:[1,0,3,2] row_mask:0xf bank_mask:0xf
	s_nop 0
	v_cndmask_b32_e32 v14, v14, v15, vcc
	v_sqrt_f32_e32 v15, v14
	s_nop 0
	v_add_u32_e32 v19, -1, v15
	v_fma_f32 v21, -v19, v15, v14
	v_cmp_ge_f32_e64 s[4:5], 0, v21
	v_add_u32_e32 v21, 1, v15
	s_nop 0
	v_cndmask_b32_e64 v19, v15, v19, s[4:5]
	v_fma_f32 v15, -v21, v15, v14
	v_cmp_lt_f32_e64 s[4:5], 0, v15
	s_nop 1
	v_cndmask_b32_e64 v15, v19, v21, s[4:5]
	v_mul_f32_e32 v19, 0x37800000, v15
	v_cndmask_b32_e32 v15, v15, v19, vcc
	v_cmp_class_f32_e32 vcc, v14, v212
	s_nop 1
	v_cndmask_b32_e32 v19, v15, v14, vcc
	v_lshl_add_u64 v[14:15], v[26:27], 0, s[20:21]
	v_mul_f32_e32 v26, v54, v20
	v_mul_f32_e32 v26, v26, v35
	v_lshlrev_b32_e32 v27, 16, v39
	v_mul_f32_e32 v26, v26, v27
	v_bfe_u32 v27, v26, 16, 1
	v_add3_u32 v26, v26, v27, s61
	global_store_short_d16_hi v[24:25], v26, off offset:64
	v_mul_f32_e32 v27, v31, v20
	v_add_u32_e32 v206, s99, v14
	v_mul_hi_u32 v207, v206, s101
	v_mul_u32_u24_e32 v207, 0x5700, v207
	v_sub_u32_e32 v206, v206, v207
	v_add_u32_e32 v206, s100, v206
	ds_read_u16 v26, v206 offset:64
	v_mul_f32_e32 v27, v27, v37
	v_mul_f32_e32 v27, v27, v30
	v_bfe_u32 v30, v27, 16, 1
	v_add3_u32 v27, v27, v30, s61
	global_store_short_d16_hi v[24:25], v27, off offset:128
	v_mul_f32_e32 v20, v33, v20
	v_add_u32_e32 v206, s99, v14
	v_mul_hi_u32 v207, v206, s101
	v_mul_u32_u24_e32 v207, 0x5700, v207
	v_sub_u32_e32 v206, v206, v207
	v_add_u32_e32 v206, s100, v206
	ds_read_u16 v27, v206 offset:128
	v_mul_f32_e32 v20, v20, v38
	v_lshlrev_b32_e32 v30, 16, v32
	v_mul_f32_e32 v20, v20, v30
	v_bfe_u32 v30, v20, 16, 1
	v_add3_u32 v20, v20, v30, s61
	global_store_short_d16_hi v[24:25], v20, off offset:192
	v_add_u32_e32 v206, s99, v14
	v_mul_hi_u32 v207, v206, s101
	v_mul_u32_u24_e32 v207, 0x5700, v207
	v_sub_u32_e32 v206, v206, v207
	v_add_u32_e32 v206, s100, v206
	ds_read_u16 v24, v206 offset:192
	v_div_scale_f32 v21, s[4:5], v19, v19, s59
	v_rcp_f32_e32 v50, v21
	v_div_scale_f32 v20, vcc, s59, v19, s59
	v_sub_f32_e32 v32, v47, v8
	v_fma_f32 v14, -v21, v50, 1.0
	v_fmac_f32_e32 v50, v14, v50
	s_waitcnt lgkmcnt(0)
; DI float bf2f(unsigned short u) { return __uint_as_float((unsigned)u << 16); }
; DI unsigned f2bf(float f) { unsigned u = __float_as_uint(f); return (u + 0x7fffu + ((u >> 16) & 1u)) >> 16; }
; DI int crow(int i, int hh) { return (i & 3) + 8 * (i >> 2) + 4 * hh; }
; DI void attn_unit(Ctx A_, LAS unsigned char* lds, int b, int h, int qb, float lam, int wave, int lane) {
;     ...
;     if (mp == 0) {
;         float ssq[16];
; #pragma unroll
;         for (int i = 0; i < 16; ++i) ssq[i] = 0.f;
; #pragma unroll
;         for (int nb = 0; nb < 4; ++nb)
; #pragma unroll
;             for (int i = 0; i < 16; ++i) { const float d = o[nb][i] - X2[(nb * 16 + i) * 64]; o[nb][i] = d; ssq[i] += d * d; }
; #pragma unroll
;         for (int i = 0; i < 16; ++i) {
;             float v = ssq[i];
; #pragma unroll
;             for (int x = 1; x < 32; x <<= 1) v += __shfl_xor(v, x);
;             ssq[i] = ONE_M_LAMINIT / sqrtf(v * (1.0f / 128.0f) + NORM_EPS);
;         }
; #pragma unroll
;         for (int nb = 0; nb < 4; ++nb) {
;             const float sn = SUB_NORM[nb * 32 + r_e];
; #pragma unroll
;             for (int i = 0; i < 16; ++i) {
;                 const size_t rw = (size_t)(rowq_e + crow(i, hh_e));
;                 Y_[rw * YLD + C_YA + h_e * 128 + nb * 32 + r_e] = (bf16)f2bf(o[nb][i] * ssq[i] * sn * bf2f(P[rw * PLD + C_ZA + h_e * 128 + nb * 32 + r_e]));
;             }
;         }
;     }
	v_add_f32_e32 v14, v53, v56
	s_nop 1
	v_mov_b32_dpp v15, v14 quad_perm:[2,3,0,1] row_mask:0xf bank_mask:0xf
	v_mul_f32_e32 v25, v20, v50
	v_fma_f32 v30, -v21, v25, v20
	v_fmac_f32_e32 v25, v30, v50
	v_fma_f32 v20, -v21, v25, v20
	s_waitcnt lgkmcnt(0)
	v_add_f32_e32 v14, v14, v15
	s_nop 1
	v_mov_b32_dpp v15, v14 row_half_mirror row_mask:0xf bank_mask:0xf
	v_div_fmas_f32 v20, v20, v50, v25
	v_div_fixup_f32 v25, v20, v19, s59
	v_mul_f32_e32 v39, v51, v25
	v_mul_f32_e32 v39, v39, v35
	s_waitcnt lgkmcnt(0)
	v_add_f32_e32 v30, v14, v15
	v_mul_f32_e32 v14, v18, v25
	v_mul_f32_e32 v14, v14, v34
	v_lshlrev_b32_e32 v15, 16, v28
	v_mul_f32_e32 v14, v14, v15
	v_bfe_u32 v15, v14, 16, 1
	v_add3_u32 v18, v14, v15, s61
	v_mad_i64_i32 v[14:15], s[4:5], v55, s62, v[4:5]
	v_add_u32_e32 v28, 25, v36
	global_store_short_d16_hi v[14:15], v18, off
	v_mad_i64_i32 v[18:19], s[4:5], v28, s57, v[6:7]
	v_lshl_add_u64 v[18:19], v[18:19], 0, s[0:1]
	v_lshl_add_u64 v[18:19], v[18:19], 0, v[2:3]
	v_add_co_u32_e32 v20, vcc, s60, v18
	v_mul_f32_e32 v22, v22, v25
	s_nop 0
	v_addc_co_u32_e32 v21, vcc, 0, v19, vcc
	v_add_u32_e32 v206, s98, v20
	v_mul_hi_u32 v207, v206, s101
	v_mul_u32_u24_e32 v207, 0x5700, v207
	v_sub_u32_e32 v206, v206, v207
	v_add_u32_e32 v206, s100, v206
	ds_read_u16 v20, v206
	v_lshl_add_u64 v[18:19], v[18:19], 0, s[20:21]
	v_mul_f32_e32 v22, v22, v38
	s_nop 1
	v_mov_b32_dpp v31, v30 row_mirror row_mask:0xf bank_mask:0xf
	v_lshlrev_b32_e32 v26, 16, v26
	v_mul_f32_e32 v26, v39, v26
	v_bfe_u32 v39, v26, 16, 1
	v_add3_u32 v26, v26, v39, s61
	global_store_short_d16_hi v[14:15], v26, off offset:64
	v_mul_f32_e32 v39, v52, v25
	v_add_u32_e32 v206, s99, v18
	v_mul_hi_u32 v207, v206, s101
	v_mul_u32_u24_e32 v207, 0x5700, v207
	v_sub_u32_e32 v206, v206, v207
	v_add_u32_e32 v206, s100, v206
	ds_read_u16 v26, v206 offset:64
	v_mul_f32_e32 v39, v39, v37
	v_lshlrev_b32_e32 v27, 16, v27
	v_mul_f32_e32 v27, v39, v27
	v_bfe_u32 v39, v27, 16, 1
	v_add3_u32 v27, v27, v39, s61
	global_store_short_d16_hi v[14:15], v27, off offset:128
	v_add_u32_e32 v206, s99, v18
	v_mul_hi_u32 v207, v206, s101
	v_mul_u32_u24_e32 v207, 0x5700, v207
	v_sub_u32_e32 v206, v206, v207
	v_add_u32_e32 v206, s100, v206
	ds_read_u16 v27, v206 offset:128
	v_lshlrev_b32_e32 v24, 16, v24
	v_mul_f32_e32 v22, v22, v24
	v_bfe_u32 v24, v22, 16, 1
	v_add3_u32 v22, v22, v24, s61
	global_store_short_d16_hi v[14:15], v22, off offset:192
	v_add_u32_e32 v206, s99, v18
	v_mul_hi_u32 v207, v206, s101
	v_mul_u32_u24_e32 v207, 0x5700, v207
	v_sub_u32_e32 v206, v206, v207
	v_add_u32_e32 v206, s100, v206
	ds_read_u16 v22, v206 offset:192
	s_waitcnt lgkmcnt(0)
	v_add_f32_e32 v21, v30, v31
	ds_bpermute_b32 v30, v209, v21
	v_sub_f32_e32 v31, v45, v10
	v_mul_f32_e32 v10, v31, v31
	v_fmac_f32_e32 v10, v16, v16
	v_fmac_f32_e32 v10, v12, v12
	s_waitcnt lgkmcnt(0)
	v_add_f32_e32 v21, v21, v30
	v_fmamk_f32 v21, v21, 0x3c000000, v211
	v_mul_f32_e32 v30, 0x4f800000, v21
	v_cmp_gt_f32_e32 vcc, s58, v21
	v_fmac_f32_e32 v10, v32, v32
	s_nop 1
	v_mov_b32_dpp v18, v10 quad_perm:[1,0,3,2] row_mask:0xf bank_mask:0xf
	v_cndmask_b32_e32 v21, v21, v30, vcc
	v_sqrt_f32_e32 v30, v21
	v_add_u32_e32 v25, 26, v36
	s_waitcnt lgkmcnt(0)
	v_add_f32_e32 v10, v10, v18
	v_add_u32_e32 v8, -1, v30
	v_fma_f32 v33, -v8, v30, v21
	v_cmp_ge_f32_e64 s[4:5], 0, v33
	v_add_u32_e32 v33, 1, v30
	v_fma_f32 v14, -v33, v30, v21
	v_cndmask_b32_e64 v8, v30, v8, s[4:5]
	v_cmp_lt_f32_e64 s[4:5], 0, v14
	s_nop 1
	v_mov_b32_dpp v18, v10 quad_perm:[2,3,0,1] row_mask:0xf bank_mask:0xf
	s_waitcnt lgkmcnt(0)
	v_add_f32_e32 v10, v10, v18
	v_cndmask_b32_e64 v8, v8, v33, s[4:5]
	v_mul_f32_e32 v14, 0x37800000, v8
	v_cndmask_b32_e32 v8, v8, v14, vcc
	v_cmp_class_f32_e32 vcc, v21, v212
	s_nop 1
	v_mov_b32_dpp v18, v10 row_half_mirror row_mask:0xf bank_mask:0xf
	s_waitcnt lgkmcnt(0)
	v_add_f32_e32 v10, v10, v18
	v_cndmask_b32_e32 v8, v8, v21, vcc
	v_div_scale_f32 v14, s[4:5], v8, v8, s59
	v_rcp_f32_e32 v15, v14
	v_lshlrev_b32_e32 v22, 16, v22
	v_fma_f32 v19, -v14, v15, 1.0
	v_fmac_f32_e32 v15, v19, v15
	v_div_scale_f32 v19, vcc, s59, v8, s59
	v_mul_f32_e32 v21, v19, v15
	v_fma_f32 v24, -v14, v21, v19
	v_fmac_f32_e32 v21, v24, v15
	v_fma_f32 v14, -v14, v21, v19
	v_div_fmas_f32 v14, v14, v15, v21
	v_div_fixup_f32 v8, v14, v8, s59
	v_mul_f32_e32 v14, v29, v8
	v_mul_f32_e32 v14, v14, v34
	v_lshlrev_b32_e32 v15, 16, v20
	v_mul_f32_e32 v14, v14, v15
	v_bfe_u32 v15, v14, 16, 1
	s_nop 1
	v_mov_b32_dpp v24, v10 row_mirror row_mask:0xf bank_mask:0xf
	v_add3_u32 v18, v14, v15, s61
	v_mad_i64_i32 v[14:15], s[4:5], v28, s62, v[4:5]
	global_store_short_d16_hi v[14:15], v18, off
	v_mad_i64_i32 v[18:19], s[4:5], v25, s57, v[6:7]
	v_lshl_add_u64 v[18:19], v[18:19], 0, s[0:1]
	v_lshl_add_u64 v[18:19], v[18:19], 0, v[2:3]
	v_add_co_u32_e32 v20, vcc, s60, v18
	s_waitcnt lgkmcnt(0)
	v_add_f32_e32 v10, v10, v24
	v_addc_co_u32_e32 v21, vcc, 0, v19, vcc
	v_add_u32_e32 v206, s98, v20
	v_mul_hi_u32 v207, v206, s101
	v_mul_u32_u24_e32 v207, 0x5700, v207
	v_sub_u32_e32 v206, v206, v207
	v_add_u32_e32 v206, s100, v206
	ds_read_u16 v20, v206
	ds_bpermute_b32 v21, v209, v10
	v_sub_f32_e32 v24, v43, v11
	s_waitcnt lgkmcnt(0)
; DI float bf2f(unsigned short u) { return __uint_as_float((unsigned)u << 16); }
; DI unsigned f2bf(float f) { unsigned u = __float_as_uint(f); return (u + 0x7fffu + ((u >> 16) & 1u)) >> 16; }
; DI int crow(int i, int hh) { return (i & 3) + 8 * (i >> 2) + 4 * hh; }
; DI int tid_now() { int t; asm volatile("v_mov_b32 %0, %1" : "=v"(t) : "v"((int)threadIdx.x)); return t; }
; #define Q_NEXT(k, id) do { if (tid == 0) qw[qit & 1] = __hip_atomic_fetch_add(qctr + 64 * (k), 1u, __ATOMIC_RELAXED, __HIP_MEMORY_SCOPE_AGENT); __syncthreads(); \
;         id = __builtin_amdgcn_readfirstlane((int)qw[qit & 1]); ++qit; } while (0)
; DI void attn_unit(Ctx A_, LAS unsigned char* lds, int b, int h, int qb, float lam, int wave, int lane) {
;     ...
;     if (mp == 0) {
;         float ssq[16];
; #pragma unroll
;         for (int i = 0; i < 16; ++i) ssq[i] = 0.f;
; #pragma unroll
;         for (int nb = 0; nb < 4; ++nb)
; #pragma unroll
;             for (int i = 0; i < 16; ++i) { const float d = o[nb][i] - X2[(nb * 16 + i) * 64]; o[nb][i] = d; ssq[i] += d * d; }
; #pragma unroll
;         for (int i = 0; i < 16; ++i) {
;             float v = ssq[i];
; #pragma unroll
;             for (int x = 1; x < 32; x <<= 1) v += __shfl_xor(v, x);
;             ssq[i] = ONE_M_LAMINIT / sqrtf(v * (1.0f / 128.0f) + NORM_EPS);
;         }
; #pragma unroll
;         for (int nb = 0; nb < 4; ++nb) {
;             const float sn = SUB_NORM[nb * 32 + r_e];
; #pragma unroll
;             for (int i = 0; i < 16; ++i) {
;                 const size_t rw = (size_t)(rowq_e + crow(i, hh_e));
;                 Y_[rw * YLD + C_YA + h_e * 128 + nb * 32 + r_e] = (bf16)f2bf(o[nb][i] * ssq[i] * sn * bf2f(P[rw * PLD + C_ZA + h_e * 128 + nb * 32 + r_e]));
;             }
;         }
;     }
; __global__ void __launch_bounds__(512, 2) fwd(Args args) {
;     ...
;         for (;;) { int id; Q_NEXT(2, id); if (id >= 2048) break; const int lane = tid_now() & 63; fa::attn_unit(A_, lds, id >> 8, (id >> 5) & 7, 31 - (id & 31), lam, wave, lane); }
	v_add_f32_e32 v10, v10, v21
	v_fmamk_f32 v21, v10, 0x3c000000, v211
	v_lshl_add_u64 v[10:11], v[18:19], 0, s[20:21]
	v_mul_f32_e32 v18, v48, v8
	v_mul_f32_e32 v18, v18, v35
	v_lshlrev_b32_e32 v19, 16, v26
	v_mul_f32_e32 v18, v18, v19
	v_bfe_u32 v19, v18, 16, 1
	v_add3_u32 v18, v18, v19, s61
	global_store_short_d16_hi v[14:15], v18, off offset:64
	v_mul_f32_e32 v19, v49, v8
	v_add_u32_e32 v206, s99, v10
	v_mul_hi_u32 v207, v206, s101
	v_mul_u32_u24_e32 v207, 0x5700, v207
	v_sub_u32_e32 v206, v206, v207
	v_add_u32_e32 v206, s100, v206
	ds_read_u16 v18, v206 offset:64
	v_mul_f32_e32 v19, v19, v37
	v_lshlrev_b32_e32 v26, 16, v27
	v_mul_f32_e32 v19, v19, v26
	v_bfe_u32 v26, v19, 16, 1
	v_add3_u32 v19, v19, v26, s61
	global_store_short_d16_hi v[14:15], v19, off offset:128
	v_mul_f32_e32 v8, v23, v8
	v_add_u32_e32 v206, s99, v10
	v_mul_hi_u32 v207, v206, s101
	v_mul_u32_u24_e32 v207, 0x5700, v207
	v_sub_u32_e32 v206, v206, v207
	v_add_u32_e32 v206, s100, v206
	ds_read_u16 v19, v206 offset:128
	v_mul_f32_e32 v8, v8, v38
	v_mul_f32_e32 v8, v8, v22
	v_bfe_u32 v22, v8, 16, 1
	v_add3_u32 v8, v8, v22, s61
	global_store_short_d16_hi v[14:15], v8, off offset:192
	v_add_u32_e32 v206, s99, v10
	v_mul_hi_u32 v207, v206, s101
	v_mul_u32_u24_e32 v207, 0x5700, v207
	v_sub_u32_e32 v206, v206, v207
	v_add_u32_e32 v206, s100, v206
	ds_read_u16 v10, v206 offset:192
	v_mul_f32_e32 v8, 0x4f800000, v21
	v_cmp_gt_f32_e32 vcc, s58, v21
	v_mul_f32_e32 v14, v24, v24
	v_fmac_f32_e32 v14, v17, v17
	v_cndmask_b32_e32 v8, v21, v8, vcc
	v_sqrt_f32_e32 v11, v8
	v_fmac_f32_e32 v14, v13, v13
	v_add_u32_e32 v15, -1, v11
	v_fma_f32 v21, -v15, v11, v8
	v_cmp_ge_f32_e64 s[4:5], 0, v21
	v_add_u32_e32 v21, 1, v11
	s_waitcnt lgkmcnt(2)
	v_lshlrev_b32_e32 v18, 16, v18
	v_cndmask_b32_e64 v15, v11, v15, s[4:5]
	v_fma_f32 v11, -v21, v11, v8
	v_cmp_lt_f32_e64 s[4:5], 0, v11
	s_waitcnt lgkmcnt(0)
	v_lshlrev_b32_e32 v10, 16, v10
	v_cndmask_b32_e64 v11, v15, v21, s[4:5]
	v_mul_f32_e32 v15, 0x37800000, v11
	v_cndmask_b32_e32 v11, v11, v15, vcc
	v_cmp_class_f32_e32 vcc, v8, v212
	v_sub_f32_e32 v21, v41, v9
	v_fmac_f32_e32 v14, v21, v21
	v_cndmask_b32_e32 v8, v11, v8, vcc
	v_div_scale_f32 v11, s[4:5], v8, v8, s59
	v_rcp_f32_e32 v15, v11
	v_div_scale_f32 v22, vcc, s59, v8, s59
	v_fma_f32 v9, -v11, v15, 1.0
	v_fmac_f32_e32 v15, v9, v15
	s_nop 1
	v_mov_b32_dpp v9, v14 quad_perm:[1,0,3,2] row_mask:0xf bank_mask:0xf
	v_mul_f32_e32 v23, v22, v15
	v_fma_f32 v26, -v11, v23, v22
	v_fmac_f32_e32 v23, v26, v15
	v_fma_f32 v11, -v11, v23, v22
	s_waitcnt lgkmcnt(0)
	v_add_f32_e32 v9, v14, v9
	s_nop 1
	v_mov_b32_dpp v14, v9 quad_perm:[2,3,0,1] row_mask:0xf bank_mask:0xf
	v_div_fmas_f32 v11, v11, v15, v23
	v_div_fixup_f32 v11, v11, v8, s59
	v_mul_f32_e32 v8, v16, v11
	v_mul_f32_e32 v8, v34, v8
	s_waitcnt lgkmcnt(0)
	v_add_f32_e32 v14, v9, v14
	v_lshlrev_b32_e32 v9, 16, v20
	v_mul_f32_e32 v8, v8, v9
	v_bfe_u32 v9, v8, 16, 1
	v_add3_u32 v16, v8, v9, s61
	v_mad_i64_i32 v[8:9], s[4:5], v25, s62, v[4:5]
	global_store_short_d16_hi v[8:9], v16, off
	v_add_u32_e32 v16, 27, v36
	v_mad_i64_i32 v[6:7], s[4:5], v16, s57, v[6:7]
	v_lshl_add_u64 v[6:7], v[6:7], 0, s[0:1]
	v_lshl_add_u64 v[2:3], v[6:7], 0, v[2:3]
	v_lshl_add_u64 v[6:7], v[2:3], 0, s[20:21]
	v_add_co_u32_e32 v2, vcc, s60, v2
	s_nop 1
	v_mov_b32_dpp v15, v14 row_half_mirror row_mask:0xf bank_mask:0xf
	s_nop 0
	v_addc_co_u32_e32 v3, vcc, 0, v3, vcc
	v_add_u32_e32 v206, s98, v2
	v_mul_hi_u32 v207, v206, s101
	v_mul_u32_u24_e32 v207, 0x5700, v207
	v_sub_u32_e32 v206, v206, v207
	v_add_u32_e32 v206, s100, v206
	ds_read_u16 v2, v206
	v_mul_f32_e32 v3, v31, v11
	v_mul_f32_e32 v3, v3, v35
	v_mul_f32_e32 v3, v3, v18
	v_bfe_u32 v18, v3, 16, 1
	v_add3_u32 v3, v3, v18, s61
	global_store_short_d16_hi v[8:9], v3, off offset:64
	v_mul_f32_e32 v3, v12, v11
	v_add_u32_e32 v206, s99, v6
	v_mul_hi_u32 v207, v206, s101
	v_mul_u32_u24_e32 v207, 0x5700, v207
	v_sub_u32_e32 v206, v206, v207
	v_add_u32_e32 v206, s100, v206
	ds_read_u16 v18, v206 offset:64
	v_mul_f32_e32 v3, v3, v37
	v_lshlrev_b32_e32 v12, 16, v19
	v_mul_f32_e32 v3, v3, v12
	v_bfe_u32 v12, v3, 16, 1
	v_add3_u32 v3, v3, v12, s61
	global_store_short_d16_hi v[8:9], v3, off offset:128
	v_mul_f32_e32 v3, v32, v11
	v_add_u32_e32 v206, s99, v6
	v_mul_hi_u32 v207, v206, s101
	v_mul_u32_u24_e32 v207, 0x5700, v207
	v_sub_u32_e32 v206, v206, v207
	v_add_u32_e32 v206, s100, v206
	ds_read_u16 v12, v206 offset:128
	v_mul_f32_e32 v3, v3, v38
	v_mul_f32_e32 v3, v3, v10
	v_bfe_u32 v10, v3, 16, 1
	v_add3_u32 v3, v3, v10, s61
	global_store_short_d16_hi v[8:9], v3, off offset:192
	v_add_u32_e32 v206, s99, v6
	v_mul_hi_u32 v207, v206, s101
	v_mul_u32_u24_e32 v207, 0x5700, v207
	v_sub_u32_e32 v206, v206, v207
	v_add_u32_e32 v206, s100, v206
	ds_read_u16 v6, v206 offset:192
	s_waitcnt lgkmcnt(0)
	v_add_f32_e32 v3, v14, v15
	s_nop 1
	v_mov_b32_dpp v7, v3 row_mirror row_mask:0xf bank_mask:0xf
	s_waitcnt lgkmcnt(0)
	v_add_f32_e32 v3, v3, v7
	ds_bpermute_b32 v7, v209, v3
	s_waitcnt lgkmcnt(0)
	v_add_f32_e32 v3, v3, v7
	v_fmamk_f32 v3, v3, 0x3c000000, v211
	v_mul_f32_e32 v7, 0x4f800000, v3
	v_cmp_gt_f32_e32 vcc, s58, v3
	v_lshlrev_b32_e32 v2, 16, v2
	v_cndmask_b32_e32 v3, v3, v7, vcc
	v_sqrt_f32_e32 v7, v3
	s_nop 0
	v_add_u32_e32 v8, -1, v7
	v_fma_f32 v9, -v8, v7, v3
	v_cmp_ge_f32_e64 s[4:5], 0, v9
	v_add_u32_e32 v9, 1, v7
	s_nop 0
	v_cndmask_b32_e64 v8, v7, v8, s[4:5]
	v_fma_f32 v7, -v9, v7, v3
	v_cmp_lt_f32_e64 s[4:5], 0, v7
	s_nop 1
	v_cndmask_b32_e64 v7, v8, v9, s[4:5]
	v_mul_f32_e32 v8, 0x37800000, v7
	v_cndmask_b32_e32 v7, v7, v8, vcc
	v_cmp_class_f32_e32 vcc, v3, v212
	s_nop 1
	v_cndmask_b32_e32 v3, v7, v3, vcc
	v_div_scale_f32 v7, s[0:1], v3, v3, s59
	v_rcp_f32_e32 v8, v7
	s_nop 0
	v_fma_f32 v9, -v7, v8, 1.0
	v_fmac_f32_e32 v8, v9, v8
	v_div_scale_f32 v9, vcc, s59, v3, s59
	v_mul_f32_e32 v10, v9, v8
	v_fma_f32 v11, -v7, v10, v9
	v_fmac_f32_e32 v10, v11, v8
	v_fma_f32 v7, -v7, v10, v9
	v_div_fmas_f32 v7, v7, v8, v10
	v_div_fixup_f32 v7, v7, v3, s59
	v_mul_f32_e32 v3, v17, v7
	v_mul_f32_e32 v3, v34, v3
	v_mul_f32_e32 v2, v3, v2
	v_bfe_u32 v3, v2, 16, 1
	v_add3_u32 v8, v2, v3, s61
	v_mad_i64_i32 v[2:3], s[0:1], v16, s62, v[4:5]
	v_mul_f32_e32 v4, v24, v7
	v_mul_f32_e32 v4, v4, v35
	v_lshlrev_b32_e32 v5, 16, v18
	v_mul_f32_e32 v4, v4, v5
	v_bfe_u32 v5, v4, 16, 1
	v_add3_u32 v4, v4, v5, s61
	global_store_short_d16_hi v[2:3], v4, off offset:64
	v_mul_f32_e32 v4, v13, v7
	v_mul_f32_e32 v4, v4, v37
	v_lshlrev_b32_e32 v5, 16, v12
	v_mul_f32_e32 v4, v4, v5
	v_bfe_u32 v5, v4, 16, 1
	v_add3_u32 v4, v4, v5, s61
	global_store_short_d16_hi v[2:3], v4, off offset:128
	v_mul_f32_e32 v4, v21, v7
	v_mul_f32_e32 v4, v4, v38
	v_lshlrev_b32_e32 v5, 16, v6
	v_mul_f32_e32 v4, v4, v5
	v_bfe_u32 v5, v4, 16, 1
	v_add3_u32 v4, v4, v5, s61
	global_store_short_d16_hi v[2:3], v8, off
	global_store_short_d16_hi v[2:3], v4, off offset:192
	s_branch .LBB0_862
